# hyena: hand-written branch-free filter-generation loop (f16 MFMA + decay + scatter into LDS), loads pipelined
# speedup vs baseline: 1.0311x; 1.0089x over previous
; __device__ __forceinline__ void phase_hyena(KP kp_, int hf){ asm volatile("" : "+s"(kp_)); const Params p=load_params(kp_);
;     ...
;     {
;       int n=lane&15, kg=lane>>4;
;       f16x8 bw0, bw1;
;       _Pragma("unroll") for (int e=0;e<8;++e){ bw0[e]=(n<4)?(_Float16)misc[(kg*8+e)*4+n]:(_Float16)0.f; bw1[e]=(n<4)?(_Float16)misc[(32+kg*8+e)*4+n]:(_Float16)0.f; }
;       const float dsc=-delta*(1.f/8191.f);
;       float pj0=__expf(dsc*(float)(kg*4)), pj1=__expf(dsc*(float)(kg*4+1)), pj2=__expf(dsc*(float)(kg*4+2)), pj3=__expf(dsc*(float)(kg*4+3));
;       float* Zf=(float*)Z; float ssl=0.f; int order=n&1; bool side1=(n&2)!=0;
;       _Pragma("unroll 8") for (int i=0;i<64;++i){ int tl=wid+8*i;
;         const _Float16* ap=a3+(size_t)(tl*16+n)*64+kg*8;
;         f16x8 a0=*(const f16x8*)ap, a1=*(const f16x8*)(ap+32);
;         f32x4 dd={0.f,0.f,0.f,0.f};
;         dd=__builtin_amdgcn_mfma_f32_16x16x32_f16(a0,bw0,dd,0,0,0);
;         dd=__builtin_amdgcn_mfma_f32_16x16x32_f16(a1,bw1,dd,0,0,0);
;         if (n<4){ float d0=__expf(dsc*(float)(tl*16)); int lag0=tl*16+kg*4;
;           float v0=dd[0]*d0*pj0, v1=dd[1]*d0*pj1, v2=dd[2]*d0*pj2, v3=dd[3]*d0*pj3;
;           if (!side1){ Zf[2*(lag0)+order]=v0; Zf[2*(lag0+1)+order]=v1; Zf[2*(lag0+2)+order]=v2; Zf[2*(lag0+3)+order]=v3; ssl+=v0*v0+v1*v1+v2*v2+v3*v3; }
;           else { if (lag0>=1){ Zf[2*(16384-lag0)+order]=v0; ssl+=v0*v0; }
;             Zf[2*(16384-lag0-1)+order]=v1; Zf[2*(16384-lag0-2)+order]=v2; Zf[2*(16384-lag0-3)+order]=v3; ssl+=v1*v1+v2*v2+v3*v3; } }
;       }
.LBB0_1232:
	s_or_b64 exec, exec, s[12:13]
	v_perm_b32 v3, v15, v3, s82
	v_perm_b32 v2, v7, v2, s82
	v_perm_b32 v1, v6, v1, s82
	v_perm_b32 v0, v5, v0, s82
	v_perm_b32 v7, v14, v13, s82
	v_perm_b32 v6, v12, v11, s82
	v_perm_b32 v5, v10, v9, s82
	v_perm_b32 v4, v8, v4, s82
	v_and_b32_e32 v29, 63, v154
	v_and_b32_e32 v30, 15, v29
	v_lshrrev_b32_e32 v31, 4, v29
	v_lshrrev_b32_e32 v25, 6, v154
	v_lshlrev_b32_e32 v24, 11, v25
	v_lshl_add_u32 v24, v30, 7, v24
	v_lshl_add_u32 v24, v31, 4, v24
	v_add_u32_e32 v24, 0x3b89000, v24
	global_load_dwordx4 v[228:231], v24, s[70:71]
	global_load_dwordx4 v[232:235], v24, s[70:71] offset:64
	v_add_u32_e32 v24, 0x4000, v24
	global_load_dwordx4 v[236:239], v24, s[70:71]
	global_load_dwordx4 v[240:243], v24, s[70:71] offset:64
	v_add_u32_e32 v24, 0x4000, v24
	global_load_dwordx4 v[244:247], v24, s[70:71]
	global_load_dwordx4 v[248:251], v24, s[70:71] offset:64
	v_add_u32_e32 v24, 0x4000, v24
	v_lshlrev_b32_e32 v18, 7, v25
	v_lshl_add_u32 v18, v31, 5, v18
	v_and_b32_e32 v17, 1, v30
	v_lshlrev_b32_e32 v17, 2, v17
	v_sub_u32_e32 v19, 0x1ffe8, v18
	v_add_u32_e32 v18, v18, v17
	v_add_u32_e32 v19, v19, v17
	v_cndmask_b32_e64 v18, v18, v19, s[40:41]
	v_mov_b32_e32 v17, 0x400
	v_mov_b32_e32 v19, 0xfffffc00
	v_cndmask_b32_e64 v19, v17, v19, s[40:41]
	v_cndmask_b32_e64 v20, v95, v50, s[40:41]
	v_cndmask_b32_e64 v21, v51, v96, s[40:41]
	v_cndmask_b32_e64 v22, v96, v51, s[40:41]
	v_cndmask_b32_e64 v23, v50, v95, s[40:41]
	v_lshrrev_b32_e32 v17, 4, v154
	v_cmp_eq_u32_e64 s[100:101], 0, v17
	s_nop 3
	s_and_b64 s[100:101], s[100:101], s[40:41]
	s_and_b64 s[100:101], s[100:101], s[38:39]
	v_mov_b32_e32 v26, 1.0
	s_nop 1
	v_cndmask_b32_e64 v26, v26, 0, s[100:101]
	s_andn2_b64 s[100:101], s[38:39], s[100:101]
	v_lshlrev_b32_e32 v25, 4, v25
	v_mov_b32_e32 v28, 0
	v_mov_b32_e32 v17, v25
	v_cvt_f32_i32_e32 v17, v17
	v_mul_f32_e32 v17, v93, v17
	v_mul_f32_e32 v17, 0x3fb8aa3b, v17
	v_exp_f32_e32 v16, v17
	s_waitcnt vmcnt(4)
	v_mfma_f32_16x16x32_f16 v[8:11], v[228:231], v[0:3], 0
	v_mfma_f32_16x16x32_f16 v[8:11], v[232:235], v[4:7], v[8:11]
	global_load_dwordx4 v[228:231], v24, s[70:71]
	global_load_dwordx4 v[232:235], v24, s[70:71] offset:64
	v_add_u32_e32 v24, 0x4000, v24
	s_nop 4
	v_cndmask_b32_e64 v12, v8, v11, s[40:41]
	v_cndmask_b32_e64 v13, v9, v10, s[40:41]
	v_cndmask_b32_e64 v14, v10, v9, s[40:41]
	v_cndmask_b32_e64 v15, v11, v8, s[40:41]
	v_mul_f32_e32 v12, v12, v16
	v_mul_f32_e32 v13, v13, v16
	v_mul_f32_e32 v14, v14, v16
	v_mul_f32_e32 v15, v15, v16
	v_mul_f32_e32 v12, v20, v12
	v_mul_f32_e32 v13, v21, v13
	v_mul_f32_e32 v14, v22, v14
	v_mul_f32_e32 v15, v23, v15
	v_mul_f32_e32 v27, v12, v12
	v_fmac_f32_e32 v27, v13, v13
	v_fmac_f32_e32 v27, v14, v14
	v_mul_f32_e32 v17, v15, v26
	v_fmac_f32_e32 v27, v17, v17
	v_add_f32_e32 v28, v28, v27
	s_mov_b64 exec, s[38:39]
	ds_write_b32 v18, v12
	ds_write_b32 v18, v13 offset:8
	ds_write_b32 v18, v14 offset:16
	s_mov_b64 exec, s[100:101]
	ds_write_b32 v18, v15 offset:24
	s_mov_b64 exec, -1
	v_add_u32_e32 v18, v18, v19
	v_add_u32_e32 v17, 0x80, v25
	v_cvt_f32_i32_e32 v17, v17
	v_mul_f32_e32 v17, v93, v17
	v_mul_f32_e32 v17, 0x3fb8aa3b, v17
	v_exp_f32_e32 v16, v17
	s_waitcnt vmcnt(4)
	v_mfma_f32_16x16x32_f16 v[8:11], v[236:239], v[0:3], 0
	v_mfma_f32_16x16x32_f16 v[8:11], v[240:243], v[4:7], v[8:11]
	global_load_dwordx4 v[236:239], v24, s[70:71]
	global_load_dwordx4 v[240:243], v24, s[70:71] offset:64
	v_add_u32_e32 v24, 0x4000, v24
	s_nop 4
	v_cndmask_b32_e64 v12, v8, v11, s[40:41]
	v_cndmask_b32_e64 v13, v9, v10, s[40:41]
	v_cndmask_b32_e64 v14, v10, v9, s[40:41]
	v_cndmask_b32_e64 v15, v11, v8, s[40:41]
	v_mul_f32_e32 v12, v12, v16
	v_mul_f32_e32 v13, v13, v16
	v_mul_f32_e32 v14, v14, v16
	v_mul_f32_e32 v15, v15, v16
	v_mul_f32_e32 v12, v20, v12
	v_mul_f32_e32 v13, v21, v13
	v_mul_f32_e32 v14, v22, v14
	v_mul_f32_e32 v15, v23, v15
	v_mul_f32_e32 v27, v12, v12
	v_fmac_f32_e32 v27, v13, v13
	v_fmac_f32_e32 v27, v14, v14
	v_fmac_f32_e32 v27, v15, v15
	v_add_f32_e32 v28, v28, v27
	s_mov_b64 exec, s[38:39]
	ds_write_b32 v18, v12
	ds_write_b32 v18, v13 offset:8
	ds_write_b32 v18, v14 offset:16
	ds_write_b32 v18, v15 offset:24
	s_mov_b64 exec, -1
	v_add_u32_e32 v18, v18, v19
	v_add_u32_e32 v17, 0x100, v25
	v_cvt_f32_i32_e32 v17, v17
	v_mul_f32_e32 v17, v93, v17
	v_mul_f32_e32 v17, 0x3fb8aa3b, v17
	v_exp_f32_e32 v16, v17
	s_waitcnt vmcnt(4)
	v_mfma_f32_16x16x32_f16 v[8:11], v[244:247], v[0:3], 0
	v_mfma_f32_16x16x32_f16 v[8:11], v[248:251], v[4:7], v[8:11]
	global_load_dwordx4 v[244:247], v24, s[70:71]
	global_load_dwordx4 v[248:251], v24, s[70:71] offset:64
	v_add_u32_e32 v24, 0x4000, v24
	s_nop 4
	v_cndmask_b32_e64 v12, v8, v11, s[40:41]
	v_cndmask_b32_e64 v13, v9, v10, s[40:41]
	v_cndmask_b32_e64 v14, v10, v9, s[40:41]
	v_cndmask_b32_e64 v15, v11, v8, s[40:41]
	v_mul_f32_e32 v12, v12, v16
	v_mul_f32_e32 v13, v13, v16
	v_mul_f32_e32 v14, v14, v16
	v_mul_f32_e32 v15, v15, v16
	v_mul_f32_e32 v12, v20, v12
	v_mul_f32_e32 v13, v21, v13
	v_mul_f32_e32 v14, v22, v14
	v_mul_f32_e32 v15, v23, v15
	v_mul_f32_e32 v27, v12, v12
	v_fmac_f32_e32 v27, v13, v13
	v_fmac_f32_e32 v27, v14, v14
	v_fmac_f32_e32 v27, v15, v15
	v_add_f32_e32 v28, v28, v27
	s_mov_b64 exec, s[38:39]
	ds_write_b32 v18, v12
	ds_write_b32 v18, v13 offset:8
	ds_write_b32 v18, v14 offset:16
	ds_write_b32 v18, v15 offset:24
	s_mov_b64 exec, -1
	v_add_u32_e32 v18, v18, v19
	v_add_u32_e32 v17, 0x180, v25
	v_cvt_f32_i32_e32 v17, v17
	v_mul_f32_e32 v17, v93, v17
	v_mul_f32_e32 v17, 0x3fb8aa3b, v17
	v_exp_f32_e32 v16, v17
	s_waitcnt vmcnt(4)
; __device__ __forceinline__ void phase_hyena(KP kp_, int hf){ asm volatile("" : "+s"(kp_)); const Params p=load_params(kp_);
;     ...
;       _Pragma("unroll 8") for (int i=0;i<64;++i){ int tl=wid+8*i;
;         const _Float16* ap=a3+(size_t)(tl*16+n)*64+kg*8;
;         f16x8 a0=*(const f16x8*)ap, a1=*(const f16x8*)(ap+32);
;         f32x4 dd={0.f,0.f,0.f,0.f};
;         dd=__builtin_amdgcn_mfma_f32_16x16x32_f16(a0,bw0,dd,0,0,0);
;         dd=__builtin_amdgcn_mfma_f32_16x16x32_f16(a1,bw1,dd,0,0,0);
;         if (n<4){ float d0=__expf(dsc*(float)(tl*16)); int lag0=tl*16+kg*4;
;           float v0=dd[0]*d0*pj0, v1=dd[1]*d0*pj1, v2=dd[2]*d0*pj2, v3=dd[3]*d0*pj3;
;           if (!side1){ Zf[2*(lag0)+order]=v0; Zf[2*(lag0+1)+order]=v1; Zf[2*(lag0+2)+order]=v2; Zf[2*(lag0+3)+order]=v3; ssl+=v0*v0+v1*v1+v2*v2+v3*v3; }
;           else { if (lag0>=1){ Zf[2*(16384-lag0)+order]=v0; ssl+=v0*v0; }
;             Zf[2*(16384-lag0-1)+order]=v1; Zf[2*(16384-lag0-2)+order]=v2; Zf[2*(16384-lag0-3)+order]=v3; ssl+=v1*v1+v2*v2+v3*v3; } }
;       }
	v_mfma_f32_16x16x32_f16 v[8:11], v[228:231], v[0:3], 0
	v_mfma_f32_16x16x32_f16 v[8:11], v[232:235], v[4:7], v[8:11]
	global_load_dwordx4 v[228:231], v24, s[70:71]
	global_load_dwordx4 v[232:235], v24, s[70:71] offset:64
	v_add_u32_e32 v24, 0x4000, v24
	s_nop 4
	v_cndmask_b32_e64 v12, v8, v11, s[40:41]
	v_cndmask_b32_e64 v13, v9, v10, s[40:41]
	v_cndmask_b32_e64 v14, v10, v9, s[40:41]
	v_cndmask_b32_e64 v15, v11, v8, s[40:41]
	v_mul_f32_e32 v12, v12, v16
	v_mul_f32_e32 v13, v13, v16
	v_mul_f32_e32 v14, v14, v16
	v_mul_f32_e32 v15, v15, v16
	v_mul_f32_e32 v12, v20, v12
	v_mul_f32_e32 v13, v21, v13
	v_mul_f32_e32 v14, v22, v14
	v_mul_f32_e32 v15, v23, v15
	v_mul_f32_e32 v27, v12, v12
	v_fmac_f32_e32 v27, v13, v13
	v_fmac_f32_e32 v27, v14, v14
	v_fmac_f32_e32 v27, v15, v15
	v_add_f32_e32 v28, v28, v27
	s_mov_b64 exec, s[38:39]
	ds_write_b32 v18, v12
	ds_write_b32 v18, v13 offset:8
	ds_write_b32 v18, v14 offset:16
	ds_write_b32 v18, v15 offset:24
	s_mov_b64 exec, -1
	v_add_u32_e32 v18, v18, v19
	v_add_u32_e32 v17, 0x200, v25
	v_cvt_f32_i32_e32 v17, v17
	v_mul_f32_e32 v17, v93, v17
	v_mul_f32_e32 v17, 0x3fb8aa3b, v17
	v_exp_f32_e32 v16, v17
	s_waitcnt vmcnt(4)
	v_mfma_f32_16x16x32_f16 v[8:11], v[236:239], v[0:3], 0
	v_mfma_f32_16x16x32_f16 v[8:11], v[240:243], v[4:7], v[8:11]
	global_load_dwordx4 v[236:239], v24, s[70:71]
	global_load_dwordx4 v[240:243], v24, s[70:71] offset:64
	v_add_u32_e32 v24, 0x4000, v24
	s_nop 4
	v_cndmask_b32_e64 v12, v8, v11, s[40:41]
	v_cndmask_b32_e64 v13, v9, v10, s[40:41]
	v_cndmask_b32_e64 v14, v10, v9, s[40:41]
	v_cndmask_b32_e64 v15, v11, v8, s[40:41]
	v_mul_f32_e32 v12, v12, v16
	v_mul_f32_e32 v13, v13, v16
	v_mul_f32_e32 v14, v14, v16
	v_mul_f32_e32 v15, v15, v16
	v_mul_f32_e32 v12, v20, v12
	v_mul_f32_e32 v13, v21, v13
	v_mul_f32_e32 v14, v22, v14
	v_mul_f32_e32 v15, v23, v15
	v_mul_f32_e32 v27, v12, v12
	v_fmac_f32_e32 v27, v13, v13
	v_fmac_f32_e32 v27, v14, v14
	v_fmac_f32_e32 v27, v15, v15
	v_add_f32_e32 v28, v28, v27
	s_mov_b64 exec, s[38:39]
	ds_write_b32 v18, v12
	ds_write_b32 v18, v13 offset:8
	ds_write_b32 v18, v14 offset:16
	ds_write_b32 v18, v15 offset:24
	s_mov_b64 exec, -1
	v_add_u32_e32 v18, v18, v19
	v_add_u32_e32 v17, 0x280, v25
	v_cvt_f32_i32_e32 v17, v17
	v_mul_f32_e32 v17, v93, v17
	v_mul_f32_e32 v17, 0x3fb8aa3b, v17
	v_exp_f32_e32 v16, v17
	s_waitcnt vmcnt(4)
	v_mfma_f32_16x16x32_f16 v[8:11], v[244:247], v[0:3], 0
	v_mfma_f32_16x16x32_f16 v[8:11], v[248:251], v[4:7], v[8:11]
	global_load_dwordx4 v[244:247], v24, s[70:71]
	global_load_dwordx4 v[248:251], v24, s[70:71] offset:64
	v_add_u32_e32 v24, 0x4000, v24
	s_nop 4
	v_cndmask_b32_e64 v12, v8, v11, s[40:41]
	v_cndmask_b32_e64 v13, v9, v10, s[40:41]
	v_cndmask_b32_e64 v14, v10, v9, s[40:41]
	v_cndmask_b32_e64 v15, v11, v8, s[40:41]
	v_mul_f32_e32 v12, v12, v16
	v_mul_f32_e32 v13, v13, v16
	v_mul_f32_e32 v14, v14, v16
	v_mul_f32_e32 v15, v15, v16
	v_mul_f32_e32 v12, v20, v12
	v_mul_f32_e32 v13, v21, v13
	v_mul_f32_e32 v14, v22, v14
	v_mul_f32_e32 v15, v23, v15
	v_mul_f32_e32 v27, v12, v12
	v_fmac_f32_e32 v27, v13, v13
	v_fmac_f32_e32 v27, v14, v14
	v_fmac_f32_e32 v27, v15, v15
	v_add_f32_e32 v28, v28, v27
	s_mov_b64 exec, s[38:39]
	ds_write_b32 v18, v12
	ds_write_b32 v18, v13 offset:8
	ds_write_b32 v18, v14 offset:16
	ds_write_b32 v18, v15 offset:24
	s_mov_b64 exec, -1
	v_add_u32_e32 v18, v18, v19
	v_add_u32_e32 v17, 0x300, v25
	v_cvt_f32_i32_e32 v17, v17
	v_mul_f32_e32 v17, v93, v17
	v_mul_f32_e32 v17, 0x3fb8aa3b, v17
	v_exp_f32_e32 v16, v17
	s_waitcnt vmcnt(4)
	v_mfma_f32_16x16x32_f16 v[8:11], v[228:231], v[0:3], 0
	v_mfma_f32_16x16x32_f16 v[8:11], v[232:235], v[4:7], v[8:11]
	global_load_dwordx4 v[228:231], v24, s[70:71]
	global_load_dwordx4 v[232:235], v24, s[70:71] offset:64
	v_add_u32_e32 v24, 0x4000, v24
	s_nop 4
	v_cndmask_b32_e64 v12, v8, v11, s[40:41]
	v_cndmask_b32_e64 v13, v9, v10, s[40:41]
	v_cndmask_b32_e64 v14, v10, v9, s[40:41]
	v_cndmask_b32_e64 v15, v11, v8, s[40:41]
	v_mul_f32_e32 v12, v12, v16
	v_mul_f32_e32 v13, v13, v16
	v_mul_f32_e32 v14, v14, v16
	v_mul_f32_e32 v15, v15, v16
	v_mul_f32_e32 v12, v20, v12
	v_mul_f32_e32 v13, v21, v13
	v_mul_f32_e32 v14, v22, v14
	v_mul_f32_e32 v15, v23, v15
	v_mul_f32_e32 v27, v12, v12
	v_fmac_f32_e32 v27, v13, v13
	v_fmac_f32_e32 v27, v14, v14
	v_fmac_f32_e32 v27, v15, v15
	v_add_f32_e32 v28, v28, v27
	s_mov_b64 exec, s[38:39]
	ds_write_b32 v18, v12
	ds_write_b32 v18, v13 offset:8
	ds_write_b32 v18, v14 offset:16
	ds_write_b32 v18, v15 offset:24
	s_mov_b64 exec, -1
	v_add_u32_e32 v18, v18, v19
	v_add_u32_e32 v17, 0x380, v25
	v_cvt_f32_i32_e32 v17, v17
	v_mul_f32_e32 v17, v93, v17
	v_mul_f32_e32 v17, 0x3fb8aa3b, v17
	v_exp_f32_e32 v16, v17
	s_waitcnt vmcnt(4)
	v_mfma_f32_16x16x32_f16 v[8:11], v[236:239], v[0:3], 0
	v_mfma_f32_16x16x32_f16 v[8:11], v[240:243], v[4:7], v[8:11]
	global_load_dwordx4 v[236:239], v24, s[70:71]
	global_load_dwordx4 v[240:243], v24, s[70:71] offset:64
	v_add_u32_e32 v24, 0x4000, v24
	s_nop 4
	v_cndmask_b32_e64 v12, v8, v11, s[40:41]
	v_cndmask_b32_e64 v13, v9, v10, s[40:41]
	v_cndmask_b32_e64 v14, v10, v9, s[40:41]
	v_cndmask_b32_e64 v15, v11, v8, s[40:41]
	v_mul_f32_e32 v12, v12, v16
	v_mul_f32_e32 v13, v13, v16
	v_mul_f32_e32 v14, v14, v16
	v_mul_f32_e32 v15, v15, v16
	v_mul_f32_e32 v12, v20, v12
	v_mul_f32_e32 v13, v21, v13
	v_mul_f32_e32 v14, v22, v14
	v_mul_f32_e32 v15, v23, v15
	v_mul_f32_e32 v27, v12, v12
	v_fmac_f32_e32 v27, v13, v13
	v_fmac_f32_e32 v27, v14, v14
	v_fmac_f32_e32 v27, v15, v15
	v_add_f32_e32 v28, v28, v27
	s_mov_b64 exec, s[38:39]
	ds_write_b32 v18, v12
	ds_write_b32 v18, v13 offset:8
	ds_write_b32 v18, v14 offset:16
	ds_write_b32 v18, v15 offset:24
	s_mov_b64 exec, -1
	v_add_u32_e32 v18, v18, v19
	v_add_u32_e32 v17, 0x400, v25
	v_cvt_f32_i32_e32 v17, v17
	v_mul_f32_e32 v17, v93, v17
	v_mul_f32_e32 v17, 0x3fb8aa3b, v17
	v_exp_f32_e32 v16, v17
	s_waitcnt vmcnt(4)
; __device__ __forceinline__ void phase_hyena(KP kp_, int hf){ asm volatile("" : "+s"(kp_)); const Params p=load_params(kp_);
;     ...
;       _Pragma("unroll 8") for (int i=0;i<64;++i){ int tl=wid+8*i;
;         const _Float16* ap=a3+(size_t)(tl*16+n)*64+kg*8;
;         f16x8 a0=*(const f16x8*)ap, a1=*(const f16x8*)(ap+32);
;         f32x4 dd={0.f,0.f,0.f,0.f};
;         dd=__builtin_amdgcn_mfma_f32_16x16x32_f16(a0,bw0,dd,0,0,0);
;         dd=__builtin_amdgcn_mfma_f32_16x16x32_f16(a1,bw1,dd,0,0,0);
;         if (n<4){ float d0=__expf(dsc*(float)(tl*16)); int lag0=tl*16+kg*4;
;           float v0=dd[0]*d0*pj0, v1=dd[1]*d0*pj1, v2=dd[2]*d0*pj2, v3=dd[3]*d0*pj3;
;           if (!side1){ Zf[2*(lag0)+order]=v0; Zf[2*(lag0+1)+order]=v1; Zf[2*(lag0+2)+order]=v2; Zf[2*(lag0+3)+order]=v3; ssl+=v0*v0+v1*v1+v2*v2+v3*v3; }
;           else { if (lag0>=1){ Zf[2*(16384-lag0)+order]=v0; ssl+=v0*v0; }
;             Zf[2*(16384-lag0-1)+order]=v1; Zf[2*(16384-lag0-2)+order]=v2; Zf[2*(16384-lag0-3)+order]=v3; ssl+=v1*v1+v2*v2+v3*v3; } }
;       }
	v_mfma_f32_16x16x32_f16 v[8:11], v[244:247], v[0:3], 0
	v_mfma_f32_16x16x32_f16 v[8:11], v[248:251], v[4:7], v[8:11]
	global_load_dwordx4 v[244:247], v24, s[70:71]
	global_load_dwordx4 v[248:251], v24, s[70:71] offset:64
	v_add_u32_e32 v24, 0x4000, v24
	s_nop 4
	v_cndmask_b32_e64 v12, v8, v11, s[40:41]
	v_cndmask_b32_e64 v13, v9, v10, s[40:41]
	v_cndmask_b32_e64 v14, v10, v9, s[40:41]
	v_cndmask_b32_e64 v15, v11, v8, s[40:41]
	v_mul_f32_e32 v12, v12, v16
	v_mul_f32_e32 v13, v13, v16
	v_mul_f32_e32 v14, v14, v16
	v_mul_f32_e32 v15, v15, v16
	v_mul_f32_e32 v12, v20, v12
	v_mul_f32_e32 v13, v21, v13
	v_mul_f32_e32 v14, v22, v14
	v_mul_f32_e32 v15, v23, v15
	v_mul_f32_e32 v27, v12, v12
	v_fmac_f32_e32 v27, v13, v13
	v_fmac_f32_e32 v27, v14, v14
	v_fmac_f32_e32 v27, v15, v15
	v_add_f32_e32 v28, v28, v27
	s_mov_b64 exec, s[38:39]
	ds_write_b32 v18, v12
	ds_write_b32 v18, v13 offset:8
	ds_write_b32 v18, v14 offset:16
	ds_write_b32 v18, v15 offset:24
	s_mov_b64 exec, -1
	v_add_u32_e32 v18, v18, v19
	v_add_u32_e32 v17, 0x480, v25
	v_cvt_f32_i32_e32 v17, v17
	v_mul_f32_e32 v17, v93, v17
	v_mul_f32_e32 v17, 0x3fb8aa3b, v17
	v_exp_f32_e32 v16, v17
	s_waitcnt vmcnt(4)
	v_mfma_f32_16x16x32_f16 v[8:11], v[228:231], v[0:3], 0
	v_mfma_f32_16x16x32_f16 v[8:11], v[232:235], v[4:7], v[8:11]
	global_load_dwordx4 v[228:231], v24, s[70:71]
	global_load_dwordx4 v[232:235], v24, s[70:71] offset:64
	v_add_u32_e32 v24, 0x4000, v24
	s_nop 4
	v_cndmask_b32_e64 v12, v8, v11, s[40:41]
	v_cndmask_b32_e64 v13, v9, v10, s[40:41]
	v_cndmask_b32_e64 v14, v10, v9, s[40:41]
	v_cndmask_b32_e64 v15, v11, v8, s[40:41]
	v_mul_f32_e32 v12, v12, v16
	v_mul_f32_e32 v13, v13, v16
	v_mul_f32_e32 v14, v14, v16
	v_mul_f32_e32 v15, v15, v16
	v_mul_f32_e32 v12, v20, v12
	v_mul_f32_e32 v13, v21, v13
	v_mul_f32_e32 v14, v22, v14
	v_mul_f32_e32 v15, v23, v15
	v_mul_f32_e32 v27, v12, v12
	v_fmac_f32_e32 v27, v13, v13
	v_fmac_f32_e32 v27, v14, v14
	v_fmac_f32_e32 v27, v15, v15
	v_add_f32_e32 v28, v28, v27
	s_mov_b64 exec, s[38:39]
	ds_write_b32 v18, v12
	ds_write_b32 v18, v13 offset:8
	ds_write_b32 v18, v14 offset:16
	ds_write_b32 v18, v15 offset:24
	s_mov_b64 exec, -1
	v_add_u32_e32 v18, v18, v19
	v_add_u32_e32 v17, 0x500, v25
	v_cvt_f32_i32_e32 v17, v17
	v_mul_f32_e32 v17, v93, v17
	v_mul_f32_e32 v17, 0x3fb8aa3b, v17
	v_exp_f32_e32 v16, v17
	s_waitcnt vmcnt(4)
	v_mfma_f32_16x16x32_f16 v[8:11], v[236:239], v[0:3], 0
	v_mfma_f32_16x16x32_f16 v[8:11], v[240:243], v[4:7], v[8:11]
	global_load_dwordx4 v[236:239], v24, s[70:71]
	global_load_dwordx4 v[240:243], v24, s[70:71] offset:64
	v_add_u32_e32 v24, 0x4000, v24
	s_nop 4
	v_cndmask_b32_e64 v12, v8, v11, s[40:41]
	v_cndmask_b32_e64 v13, v9, v10, s[40:41]
	v_cndmask_b32_e64 v14, v10, v9, s[40:41]
	v_cndmask_b32_e64 v15, v11, v8, s[40:41]
	v_mul_f32_e32 v12, v12, v16
	v_mul_f32_e32 v13, v13, v16
	v_mul_f32_e32 v14, v14, v16
	v_mul_f32_e32 v15, v15, v16
	v_mul_f32_e32 v12, v20, v12
	v_mul_f32_e32 v13, v21, v13
	v_mul_f32_e32 v14, v22, v14
	v_mul_f32_e32 v15, v23, v15
	v_mul_f32_e32 v27, v12, v12
	v_fmac_f32_e32 v27, v13, v13
	v_fmac_f32_e32 v27, v14, v14
	v_fmac_f32_e32 v27, v15, v15
	v_add_f32_e32 v28, v28, v27
	s_mov_b64 exec, s[38:39]
	ds_write_b32 v18, v12
	ds_write_b32 v18, v13 offset:8
	ds_write_b32 v18, v14 offset:16
	ds_write_b32 v18, v15 offset:24
	s_mov_b64 exec, -1
	v_add_u32_e32 v18, v18, v19
	v_add_u32_e32 v17, 0x580, v25
	v_cvt_f32_i32_e32 v17, v17
	v_mul_f32_e32 v17, v93, v17
	v_mul_f32_e32 v17, 0x3fb8aa3b, v17
	v_exp_f32_e32 v16, v17
	s_waitcnt vmcnt(4)
	v_mfma_f32_16x16x32_f16 v[8:11], v[244:247], v[0:3], 0
	v_mfma_f32_16x16x32_f16 v[8:11], v[248:251], v[4:7], v[8:11]
	global_load_dwordx4 v[244:247], v24, s[70:71]
	global_load_dwordx4 v[248:251], v24, s[70:71] offset:64
	v_add_u32_e32 v24, 0x4000, v24
	s_nop 4
	v_cndmask_b32_e64 v12, v8, v11, s[40:41]
	v_cndmask_b32_e64 v13, v9, v10, s[40:41]
	v_cndmask_b32_e64 v14, v10, v9, s[40:41]
	v_cndmask_b32_e64 v15, v11, v8, s[40:41]
	v_mul_f32_e32 v12, v12, v16
	v_mul_f32_e32 v13, v13, v16
	v_mul_f32_e32 v14, v14, v16
	v_mul_f32_e32 v15, v15, v16
	v_mul_f32_e32 v12, v20, v12
	v_mul_f32_e32 v13, v21, v13
	v_mul_f32_e32 v14, v22, v14
	v_mul_f32_e32 v15, v23, v15
	v_mul_f32_e32 v27, v12, v12
	v_fmac_f32_e32 v27, v13, v13
	v_fmac_f32_e32 v27, v14, v14
	v_fmac_f32_e32 v27, v15, v15
	v_add_f32_e32 v28, v28, v27
	s_mov_b64 exec, s[38:39]
	ds_write_b32 v18, v12
	ds_write_b32 v18, v13 offset:8
	ds_write_b32 v18, v14 offset:16
	ds_write_b32 v18, v15 offset:24
	s_mov_b64 exec, -1
	v_add_u32_e32 v18, v18, v19
	v_add_u32_e32 v17, 0x600, v25
	v_cvt_f32_i32_e32 v17, v17
	v_mul_f32_e32 v17, v93, v17
	v_mul_f32_e32 v17, 0x3fb8aa3b, v17
	v_exp_f32_e32 v16, v17
	s_waitcnt vmcnt(4)
	v_mfma_f32_16x16x32_f16 v[8:11], v[228:231], v[0:3], 0
	v_mfma_f32_16x16x32_f16 v[8:11], v[232:235], v[4:7], v[8:11]
	global_load_dwordx4 v[228:231], v24, s[70:71]
	global_load_dwordx4 v[232:235], v24, s[70:71] offset:64
	v_add_u32_e32 v24, 0x4000, v24
	s_nop 4
	v_cndmask_b32_e64 v12, v8, v11, s[40:41]
	v_cndmask_b32_e64 v13, v9, v10, s[40:41]
	v_cndmask_b32_e64 v14, v10, v9, s[40:41]
	v_cndmask_b32_e64 v15, v11, v8, s[40:41]
	v_mul_f32_e32 v12, v12, v16
	v_mul_f32_e32 v13, v13, v16
	v_mul_f32_e32 v14, v14, v16
	v_mul_f32_e32 v15, v15, v16
	v_mul_f32_e32 v12, v20, v12
	v_mul_f32_e32 v13, v21, v13
	v_mul_f32_e32 v14, v22, v14
	v_mul_f32_e32 v15, v23, v15
	v_mul_f32_e32 v27, v12, v12
	v_fmac_f32_e32 v27, v13, v13
	v_fmac_f32_e32 v27, v14, v14
	v_fmac_f32_e32 v27, v15, v15
	v_add_f32_e32 v28, v28, v27
	s_mov_b64 exec, s[38:39]
	ds_write_b32 v18, v12
	ds_write_b32 v18, v13 offset:8
	ds_write_b32 v18, v14 offset:16
	ds_write_b32 v18, v15 offset:24
	s_mov_b64 exec, -1
	v_add_u32_e32 v18, v18, v19
	v_add_u32_e32 v17, 0x680, v25
	v_cvt_f32_i32_e32 v17, v17
	v_mul_f32_e32 v17, v93, v17
	v_mul_f32_e32 v17, 0x3fb8aa3b, v17
	v_exp_f32_e32 v16, v17
	s_waitcnt vmcnt(4)
; __device__ __forceinline__ void phase_hyena(KP kp_, int hf){ asm volatile("" : "+s"(kp_)); const Params p=load_params(kp_);
;     ...
;       _Pragma("unroll 8") for (int i=0;i<64;++i){ int tl=wid+8*i;
;         const _Float16* ap=a3+(size_t)(tl*16+n)*64+kg*8;
;         f16x8 a0=*(const f16x8*)ap, a1=*(const f16x8*)(ap+32);
;         f32x4 dd={0.f,0.f,0.f,0.f};
;         dd=__builtin_amdgcn_mfma_f32_16x16x32_f16(a0,bw0,dd,0,0,0);
;         dd=__builtin_amdgcn_mfma_f32_16x16x32_f16(a1,bw1,dd,0,0,0);
;         if (n<4){ float d0=__expf(dsc*(float)(tl*16)); int lag0=tl*16+kg*4;
;           float v0=dd[0]*d0*pj0, v1=dd[1]*d0*pj1, v2=dd[2]*d0*pj2, v3=dd[3]*d0*pj3;
;           if (!side1){ Zf[2*(lag0)+order]=v0; Zf[2*(lag0+1)+order]=v1; Zf[2*(lag0+2)+order]=v2; Zf[2*(lag0+3)+order]=v3; ssl+=v0*v0+v1*v1+v2*v2+v3*v3; }
;           else { if (lag0>=1){ Zf[2*(16384-lag0)+order]=v0; ssl+=v0*v0; }
;             Zf[2*(16384-lag0-1)+order]=v1; Zf[2*(16384-lag0-2)+order]=v2; Zf[2*(16384-lag0-3)+order]=v3; ssl+=v1*v1+v2*v2+v3*v3; } }
;       }
	v_mfma_f32_16x16x32_f16 v[8:11], v[236:239], v[0:3], 0
	v_mfma_f32_16x16x32_f16 v[8:11], v[240:243], v[4:7], v[8:11]
	global_load_dwordx4 v[236:239], v24, s[70:71]
	global_load_dwordx4 v[240:243], v24, s[70:71] offset:64
	v_add_u32_e32 v24, 0x4000, v24
	s_nop 4
	v_cndmask_b32_e64 v12, v8, v11, s[40:41]
	v_cndmask_b32_e64 v13, v9, v10, s[40:41]
	v_cndmask_b32_e64 v14, v10, v9, s[40:41]
	v_cndmask_b32_e64 v15, v11, v8, s[40:41]
	v_mul_f32_e32 v12, v12, v16
	v_mul_f32_e32 v13, v13, v16
	v_mul_f32_e32 v14, v14, v16
	v_mul_f32_e32 v15, v15, v16
	v_mul_f32_e32 v12, v20, v12
	v_mul_f32_e32 v13, v21, v13
	v_mul_f32_e32 v14, v22, v14
	v_mul_f32_e32 v15, v23, v15
	v_mul_f32_e32 v27, v12, v12
	v_fmac_f32_e32 v27, v13, v13
	v_fmac_f32_e32 v27, v14, v14
	v_fmac_f32_e32 v27, v15, v15
	v_add_f32_e32 v28, v28, v27
	s_mov_b64 exec, s[38:39]
	ds_write_b32 v18, v12
	ds_write_b32 v18, v13 offset:8
	ds_write_b32 v18, v14 offset:16
	ds_write_b32 v18, v15 offset:24
	s_mov_b64 exec, -1
	v_add_u32_e32 v18, v18, v19
	v_add_u32_e32 v17, 0x700, v25
	v_cvt_f32_i32_e32 v17, v17
	v_mul_f32_e32 v17, v93, v17
	v_mul_f32_e32 v17, 0x3fb8aa3b, v17
	v_exp_f32_e32 v16, v17
	s_waitcnt vmcnt(4)
	v_mfma_f32_16x16x32_f16 v[8:11], v[244:247], v[0:3], 0
	v_mfma_f32_16x16x32_f16 v[8:11], v[248:251], v[4:7], v[8:11]
	global_load_dwordx4 v[244:247], v24, s[70:71]
	global_load_dwordx4 v[248:251], v24, s[70:71] offset:64
	v_add_u32_e32 v24, 0x4000, v24
	s_nop 4
	v_cndmask_b32_e64 v12, v8, v11, s[40:41]
	v_cndmask_b32_e64 v13, v9, v10, s[40:41]
	v_cndmask_b32_e64 v14, v10, v9, s[40:41]
	v_cndmask_b32_e64 v15, v11, v8, s[40:41]
	v_mul_f32_e32 v12, v12, v16
	v_mul_f32_e32 v13, v13, v16
	v_mul_f32_e32 v14, v14, v16
	v_mul_f32_e32 v15, v15, v16
	v_mul_f32_e32 v12, v20, v12
	v_mul_f32_e32 v13, v21, v13
	v_mul_f32_e32 v14, v22, v14
	v_mul_f32_e32 v15, v23, v15
	v_mul_f32_e32 v27, v12, v12
	v_fmac_f32_e32 v27, v13, v13
	v_fmac_f32_e32 v27, v14, v14
	v_fmac_f32_e32 v27, v15, v15
	v_add_f32_e32 v28, v28, v27
	s_mov_b64 exec, s[38:39]
	ds_write_b32 v18, v12
	ds_write_b32 v18, v13 offset:8
	ds_write_b32 v18, v14 offset:16
	ds_write_b32 v18, v15 offset:24
	s_mov_b64 exec, -1
	v_add_u32_e32 v18, v18, v19
	v_add_u32_e32 v17, 0x780, v25
	v_cvt_f32_i32_e32 v17, v17
	v_mul_f32_e32 v17, v93, v17
	v_mul_f32_e32 v17, 0x3fb8aa3b, v17
	v_exp_f32_e32 v16, v17
	s_waitcnt vmcnt(4)
	v_mfma_f32_16x16x32_f16 v[8:11], v[228:231], v[0:3], 0
	v_mfma_f32_16x16x32_f16 v[8:11], v[232:235], v[4:7], v[8:11]
	global_load_dwordx4 v[228:231], v24, s[70:71]
	global_load_dwordx4 v[232:235], v24, s[70:71] offset:64
	v_add_u32_e32 v24, 0x4000, v24
	s_nop 4
	v_cndmask_b32_e64 v12, v8, v11, s[40:41]
	v_cndmask_b32_e64 v13, v9, v10, s[40:41]
	v_cndmask_b32_e64 v14, v10, v9, s[40:41]
	v_cndmask_b32_e64 v15, v11, v8, s[40:41]
	v_mul_f32_e32 v12, v12, v16
	v_mul_f32_e32 v13, v13, v16
	v_mul_f32_e32 v14, v14, v16
	v_mul_f32_e32 v15, v15, v16
	v_mul_f32_e32 v12, v20, v12
	v_mul_f32_e32 v13, v21, v13
	v_mul_f32_e32 v14, v22, v14
	v_mul_f32_e32 v15, v23, v15
	v_mul_f32_e32 v27, v12, v12
	v_fmac_f32_e32 v27, v13, v13
	v_fmac_f32_e32 v27, v14, v14
	v_fmac_f32_e32 v27, v15, v15
	v_add_f32_e32 v28, v28, v27
	s_mov_b64 exec, s[38:39]
	ds_write_b32 v18, v12
	ds_write_b32 v18, v13 offset:8
	ds_write_b32 v18, v14 offset:16
	ds_write_b32 v18, v15 offset:24
	s_mov_b64 exec, -1
	v_add_u32_e32 v18, v18, v19
	v_add_u32_e32 v17, 0x800, v25
	v_cvt_f32_i32_e32 v17, v17
	v_mul_f32_e32 v17, v93, v17
	v_mul_f32_e32 v17, 0x3fb8aa3b, v17
	v_exp_f32_e32 v16, v17
	s_waitcnt vmcnt(4)
	v_mfma_f32_16x16x32_f16 v[8:11], v[236:239], v[0:3], 0
	v_mfma_f32_16x16x32_f16 v[8:11], v[240:243], v[4:7], v[8:11]
	global_load_dwordx4 v[236:239], v24, s[70:71]
	global_load_dwordx4 v[240:243], v24, s[70:71] offset:64
	v_add_u32_e32 v24, 0x4000, v24
	s_nop 4
	v_cndmask_b32_e64 v12, v8, v11, s[40:41]
	v_cndmask_b32_e64 v13, v9, v10, s[40:41]
	v_cndmask_b32_e64 v14, v10, v9, s[40:41]
	v_cndmask_b32_e64 v15, v11, v8, s[40:41]
	v_mul_f32_e32 v12, v12, v16
	v_mul_f32_e32 v13, v13, v16
	v_mul_f32_e32 v14, v14, v16
	v_mul_f32_e32 v15, v15, v16
	v_mul_f32_e32 v12, v20, v12
	v_mul_f32_e32 v13, v21, v13
	v_mul_f32_e32 v14, v22, v14
	v_mul_f32_e32 v15, v23, v15
	v_mul_f32_e32 v27, v12, v12
	v_fmac_f32_e32 v27, v13, v13
	v_fmac_f32_e32 v27, v14, v14
	v_fmac_f32_e32 v27, v15, v15
	v_add_f32_e32 v28, v28, v27
	s_mov_b64 exec, s[38:39]
	ds_write_b32 v18, v12
	ds_write_b32 v18, v13 offset:8
	ds_write_b32 v18, v14 offset:16
	ds_write_b32 v18, v15 offset:24
	s_mov_b64 exec, -1
	v_add_u32_e32 v18, v18, v19
	v_add_u32_e32 v17, 0x880, v25
	v_cvt_f32_i32_e32 v17, v17
	v_mul_f32_e32 v17, v93, v17
	v_mul_f32_e32 v17, 0x3fb8aa3b, v17
	v_exp_f32_e32 v16, v17
	s_waitcnt vmcnt(4)
	v_mfma_f32_16x16x32_f16 v[8:11], v[244:247], v[0:3], 0
	v_mfma_f32_16x16x32_f16 v[8:11], v[248:251], v[4:7], v[8:11]
	global_load_dwordx4 v[244:247], v24, s[70:71]
	global_load_dwordx4 v[248:251], v24, s[70:71] offset:64
	v_add_u32_e32 v24, 0x4000, v24
	s_nop 4
	v_cndmask_b32_e64 v12, v8, v11, s[40:41]
	v_cndmask_b32_e64 v13, v9, v10, s[40:41]
	v_cndmask_b32_e64 v14, v10, v9, s[40:41]
	v_cndmask_b32_e64 v15, v11, v8, s[40:41]
	v_mul_f32_e32 v12, v12, v16
	v_mul_f32_e32 v13, v13, v16
	v_mul_f32_e32 v14, v14, v16
	v_mul_f32_e32 v15, v15, v16
	v_mul_f32_e32 v12, v20, v12
	v_mul_f32_e32 v13, v21, v13
	v_mul_f32_e32 v14, v22, v14
	v_mul_f32_e32 v15, v23, v15
	v_mul_f32_e32 v27, v12, v12
	v_fmac_f32_e32 v27, v13, v13
	v_fmac_f32_e32 v27, v14, v14
	v_fmac_f32_e32 v27, v15, v15
	v_add_f32_e32 v28, v28, v27
	s_mov_b64 exec, s[38:39]
	ds_write_b32 v18, v12
	ds_write_b32 v18, v13 offset:8
	ds_write_b32 v18, v14 offset:16
	ds_write_b32 v18, v15 offset:24
	s_mov_b64 exec, -1
	v_add_u32_e32 v18, v18, v19
	v_add_u32_e32 v17, 0x900, v25
	v_cvt_f32_i32_e32 v17, v17
	v_mul_f32_e32 v17, v93, v17
	v_mul_f32_e32 v17, 0x3fb8aa3b, v17
	v_exp_f32_e32 v16, v17
	s_waitcnt vmcnt(4)
; __device__ __forceinline__ void phase_hyena(KP kp_, int hf){ asm volatile("" : "+s"(kp_)); const Params p=load_params(kp_);
;     ...
;       _Pragma("unroll 8") for (int i=0;i<64;++i){ int tl=wid+8*i;
;         const _Float16* ap=a3+(size_t)(tl*16+n)*64+kg*8;
;         f16x8 a0=*(const f16x8*)ap, a1=*(const f16x8*)(ap+32);
;         f32x4 dd={0.f,0.f,0.f,0.f};
;         dd=__builtin_amdgcn_mfma_f32_16x16x32_f16(a0,bw0,dd,0,0,0);
;         dd=__builtin_amdgcn_mfma_f32_16x16x32_f16(a1,bw1,dd,0,0,0);
;         if (n<4){ float d0=__expf(dsc*(float)(tl*16)); int lag0=tl*16+kg*4;
;           float v0=dd[0]*d0*pj0, v1=dd[1]*d0*pj1, v2=dd[2]*d0*pj2, v3=dd[3]*d0*pj3;
;           if (!side1){ Zf[2*(lag0)+order]=v0; Zf[2*(lag0+1)+order]=v1; Zf[2*(lag0+2)+order]=v2; Zf[2*(lag0+3)+order]=v3; ssl+=v0*v0+v1*v1+v2*v2+v3*v3; }
;           else { if (lag0>=1){ Zf[2*(16384-lag0)+order]=v0; ssl+=v0*v0; }
;             Zf[2*(16384-lag0-1)+order]=v1; Zf[2*(16384-lag0-2)+order]=v2; Zf[2*(16384-lag0-3)+order]=v3; ssl+=v1*v1+v2*v2+v3*v3; } }
;       }
	v_mfma_f32_16x16x32_f16 v[8:11], v[228:231], v[0:3], 0
	v_mfma_f32_16x16x32_f16 v[8:11], v[232:235], v[4:7], v[8:11]
	global_load_dwordx4 v[228:231], v24, s[70:71]
	global_load_dwordx4 v[232:235], v24, s[70:71] offset:64
	v_add_u32_e32 v24, 0x4000, v24
	s_nop 4
	v_cndmask_b32_e64 v12, v8, v11, s[40:41]
	v_cndmask_b32_e64 v13, v9, v10, s[40:41]
	v_cndmask_b32_e64 v14, v10, v9, s[40:41]
	v_cndmask_b32_e64 v15, v11, v8, s[40:41]
	v_mul_f32_e32 v12, v12, v16
	v_mul_f32_e32 v13, v13, v16
	v_mul_f32_e32 v14, v14, v16
	v_mul_f32_e32 v15, v15, v16
	v_mul_f32_e32 v12, v20, v12
	v_mul_f32_e32 v13, v21, v13
	v_mul_f32_e32 v14, v22, v14
	v_mul_f32_e32 v15, v23, v15
	v_mul_f32_e32 v27, v12, v12
	v_fmac_f32_e32 v27, v13, v13
	v_fmac_f32_e32 v27, v14, v14
	v_fmac_f32_e32 v27, v15, v15
	v_add_f32_e32 v28, v28, v27
	s_mov_b64 exec, s[38:39]
	ds_write_b32 v18, v12
	ds_write_b32 v18, v13 offset:8
	ds_write_b32 v18, v14 offset:16
	ds_write_b32 v18, v15 offset:24
	s_mov_b64 exec, -1
	v_add_u32_e32 v18, v18, v19
	v_add_u32_e32 v17, 0x980, v25
	v_cvt_f32_i32_e32 v17, v17
	v_mul_f32_e32 v17, v93, v17
	v_mul_f32_e32 v17, 0x3fb8aa3b, v17
	v_exp_f32_e32 v16, v17
	s_waitcnt vmcnt(4)
	v_mfma_f32_16x16x32_f16 v[8:11], v[236:239], v[0:3], 0
	v_mfma_f32_16x16x32_f16 v[8:11], v[240:243], v[4:7], v[8:11]
	global_load_dwordx4 v[236:239], v24, s[70:71]
	global_load_dwordx4 v[240:243], v24, s[70:71] offset:64
	v_add_u32_e32 v24, 0x4000, v24
	s_nop 4
	v_cndmask_b32_e64 v12, v8, v11, s[40:41]
	v_cndmask_b32_e64 v13, v9, v10, s[40:41]
	v_cndmask_b32_e64 v14, v10, v9, s[40:41]
	v_cndmask_b32_e64 v15, v11, v8, s[40:41]
	v_mul_f32_e32 v12, v12, v16
	v_mul_f32_e32 v13, v13, v16
	v_mul_f32_e32 v14, v14, v16
	v_mul_f32_e32 v15, v15, v16
	v_mul_f32_e32 v12, v20, v12
	v_mul_f32_e32 v13, v21, v13
	v_mul_f32_e32 v14, v22, v14
	v_mul_f32_e32 v15, v23, v15
	v_mul_f32_e32 v27, v12, v12
	v_fmac_f32_e32 v27, v13, v13
	v_fmac_f32_e32 v27, v14, v14
	v_fmac_f32_e32 v27, v15, v15
	v_add_f32_e32 v28, v28, v27
	s_mov_b64 exec, s[38:39]
	ds_write_b32 v18, v12
	ds_write_b32 v18, v13 offset:8
	ds_write_b32 v18, v14 offset:16
	ds_write_b32 v18, v15 offset:24
	s_mov_b64 exec, -1
	v_add_u32_e32 v18, v18, v19
	v_add_u32_e32 v17, 0xa00, v25
	v_cvt_f32_i32_e32 v17, v17
	v_mul_f32_e32 v17, v93, v17
	v_mul_f32_e32 v17, 0x3fb8aa3b, v17
	v_exp_f32_e32 v16, v17
	s_waitcnt vmcnt(4)
	v_mfma_f32_16x16x32_f16 v[8:11], v[244:247], v[0:3], 0
	v_mfma_f32_16x16x32_f16 v[8:11], v[248:251], v[4:7], v[8:11]
	global_load_dwordx4 v[244:247], v24, s[70:71]
	global_load_dwordx4 v[248:251], v24, s[70:71] offset:64
	v_add_u32_e32 v24, 0x4000, v24
	s_nop 4
	v_cndmask_b32_e64 v12, v8, v11, s[40:41]
	v_cndmask_b32_e64 v13, v9, v10, s[40:41]
	v_cndmask_b32_e64 v14, v10, v9, s[40:41]
	v_cndmask_b32_e64 v15, v11, v8, s[40:41]
	v_mul_f32_e32 v12, v12, v16
	v_mul_f32_e32 v13, v13, v16
	v_mul_f32_e32 v14, v14, v16
	v_mul_f32_e32 v15, v15, v16
	v_mul_f32_e32 v12, v20, v12
	v_mul_f32_e32 v13, v21, v13
	v_mul_f32_e32 v14, v22, v14
	v_mul_f32_e32 v15, v23, v15
	v_mul_f32_e32 v27, v12, v12
	v_fmac_f32_e32 v27, v13, v13
	v_fmac_f32_e32 v27, v14, v14
	v_fmac_f32_e32 v27, v15, v15
	v_add_f32_e32 v28, v28, v27
	s_mov_b64 exec, s[38:39]
	ds_write_b32 v18, v12
	ds_write_b32 v18, v13 offset:8
	ds_write_b32 v18, v14 offset:16
	ds_write_b32 v18, v15 offset:24
	s_mov_b64 exec, -1
	v_add_u32_e32 v18, v18, v19
	v_add_u32_e32 v17, 0xa80, v25
	v_cvt_f32_i32_e32 v17, v17
	v_mul_f32_e32 v17, v93, v17
	v_mul_f32_e32 v17, 0x3fb8aa3b, v17
	v_exp_f32_e32 v16, v17
	s_waitcnt vmcnt(4)
	v_mfma_f32_16x16x32_f16 v[8:11], v[228:231], v[0:3], 0
	v_mfma_f32_16x16x32_f16 v[8:11], v[232:235], v[4:7], v[8:11]
	global_load_dwordx4 v[228:231], v24, s[70:71]
	global_load_dwordx4 v[232:235], v24, s[70:71] offset:64
	v_add_u32_e32 v24, 0x4000, v24
	s_nop 4
	v_cndmask_b32_e64 v12, v8, v11, s[40:41]
	v_cndmask_b32_e64 v13, v9, v10, s[40:41]
	v_cndmask_b32_e64 v14, v10, v9, s[40:41]
	v_cndmask_b32_e64 v15, v11, v8, s[40:41]
	v_mul_f32_e32 v12, v12, v16
	v_mul_f32_e32 v13, v13, v16
	v_mul_f32_e32 v14, v14, v16
	v_mul_f32_e32 v15, v15, v16
	v_mul_f32_e32 v12, v20, v12
	v_mul_f32_e32 v13, v21, v13
	v_mul_f32_e32 v14, v22, v14
	v_mul_f32_e32 v15, v23, v15
	v_mul_f32_e32 v27, v12, v12
	v_fmac_f32_e32 v27, v13, v13
	v_fmac_f32_e32 v27, v14, v14
	v_fmac_f32_e32 v27, v15, v15
	v_add_f32_e32 v28, v28, v27
	s_mov_b64 exec, s[38:39]
	ds_write_b32 v18, v12
	ds_write_b32 v18, v13 offset:8
	ds_write_b32 v18, v14 offset:16
	ds_write_b32 v18, v15 offset:24
	s_mov_b64 exec, -1
	v_add_u32_e32 v18, v18, v19
	v_add_u32_e32 v17, 0xb00, v25
	v_cvt_f32_i32_e32 v17, v17
	v_mul_f32_e32 v17, v93, v17
	v_mul_f32_e32 v17, 0x3fb8aa3b, v17
	v_exp_f32_e32 v16, v17
	s_waitcnt vmcnt(4)
	v_mfma_f32_16x16x32_f16 v[8:11], v[236:239], v[0:3], 0
	v_mfma_f32_16x16x32_f16 v[8:11], v[240:243], v[4:7], v[8:11]
	global_load_dwordx4 v[236:239], v24, s[70:71]
	global_load_dwordx4 v[240:243], v24, s[70:71] offset:64
	v_add_u32_e32 v24, 0x4000, v24
	s_nop 4
	v_cndmask_b32_e64 v12, v8, v11, s[40:41]
	v_cndmask_b32_e64 v13, v9, v10, s[40:41]
	v_cndmask_b32_e64 v14, v10, v9, s[40:41]
	v_cndmask_b32_e64 v15, v11, v8, s[40:41]
	v_mul_f32_e32 v12, v12, v16
	v_mul_f32_e32 v13, v13, v16
	v_mul_f32_e32 v14, v14, v16
	v_mul_f32_e32 v15, v15, v16
	v_mul_f32_e32 v12, v20, v12
	v_mul_f32_e32 v13, v21, v13
	v_mul_f32_e32 v14, v22, v14
	v_mul_f32_e32 v15, v23, v15
	v_mul_f32_e32 v27, v12, v12
	v_fmac_f32_e32 v27, v13, v13
	v_fmac_f32_e32 v27, v14, v14
	v_fmac_f32_e32 v27, v15, v15
	v_add_f32_e32 v28, v28, v27
	s_mov_b64 exec, s[38:39]
	ds_write_b32 v18, v12
	ds_write_b32 v18, v13 offset:8
	ds_write_b32 v18, v14 offset:16
	ds_write_b32 v18, v15 offset:24
	s_mov_b64 exec, -1
	v_add_u32_e32 v18, v18, v19
	v_add_u32_e32 v17, 0xb80, v25
	v_cvt_f32_i32_e32 v17, v17
	v_mul_f32_e32 v17, v93, v17
	v_mul_f32_e32 v17, 0x3fb8aa3b, v17
	v_exp_f32_e32 v16, v17
	s_waitcnt vmcnt(4)
; __device__ __forceinline__ void phase_hyena(KP kp_, int hf){ asm volatile("" : "+s"(kp_)); const Params p=load_params(kp_);
;     ...
;       _Pragma("unroll 8") for (int i=0;i<64;++i){ int tl=wid+8*i;
;         const _Float16* ap=a3+(size_t)(tl*16+n)*64+kg*8;
;         f16x8 a0=*(const f16x8*)ap, a1=*(const f16x8*)(ap+32);
;         f32x4 dd={0.f,0.f,0.f,0.f};
;         dd=__builtin_amdgcn_mfma_f32_16x16x32_f16(a0,bw0,dd,0,0,0);
;         dd=__builtin_amdgcn_mfma_f32_16x16x32_f16(a1,bw1,dd,0,0,0);
;         if (n<4){ float d0=__expf(dsc*(float)(tl*16)); int lag0=tl*16+kg*4;
;           float v0=dd[0]*d0*pj0, v1=dd[1]*d0*pj1, v2=dd[2]*d0*pj2, v3=dd[3]*d0*pj3;
;           if (!side1){ Zf[2*(lag0)+order]=v0; Zf[2*(lag0+1)+order]=v1; Zf[2*(lag0+2)+order]=v2; Zf[2*(lag0+3)+order]=v3; ssl+=v0*v0+v1*v1+v2*v2+v3*v3; }
;           else { if (lag0>=1){ Zf[2*(16384-lag0)+order]=v0; ssl+=v0*v0; }
;             Zf[2*(16384-lag0-1)+order]=v1; Zf[2*(16384-lag0-2)+order]=v2; Zf[2*(16384-lag0-3)+order]=v3; ssl+=v1*v1+v2*v2+v3*v3; } }
;       }
	v_mfma_f32_16x16x32_f16 v[8:11], v[244:247], v[0:3], 0
	v_mfma_f32_16x16x32_f16 v[8:11], v[248:251], v[4:7], v[8:11]
	global_load_dwordx4 v[244:247], v24, s[70:71]
	global_load_dwordx4 v[248:251], v24, s[70:71] offset:64
	v_add_u32_e32 v24, 0x4000, v24
	s_nop 4
	v_cndmask_b32_e64 v12, v8, v11, s[40:41]
	v_cndmask_b32_e64 v13, v9, v10, s[40:41]
	v_cndmask_b32_e64 v14, v10, v9, s[40:41]
	v_cndmask_b32_e64 v15, v11, v8, s[40:41]
	v_mul_f32_e32 v12, v12, v16
	v_mul_f32_e32 v13, v13, v16
	v_mul_f32_e32 v14, v14, v16
	v_mul_f32_e32 v15, v15, v16
	v_mul_f32_e32 v12, v20, v12
	v_mul_f32_e32 v13, v21, v13
	v_mul_f32_e32 v14, v22, v14
	v_mul_f32_e32 v15, v23, v15
	v_mul_f32_e32 v27, v12, v12
	v_fmac_f32_e32 v27, v13, v13
	v_fmac_f32_e32 v27, v14, v14
	v_fmac_f32_e32 v27, v15, v15
	v_add_f32_e32 v28, v28, v27
	s_mov_b64 exec, s[38:39]
	ds_write_b32 v18, v12
	ds_write_b32 v18, v13 offset:8
	ds_write_b32 v18, v14 offset:16
	ds_write_b32 v18, v15 offset:24
	s_mov_b64 exec, -1
	v_add_u32_e32 v18, v18, v19
	v_add_u32_e32 v17, 0xc00, v25
	v_cvt_f32_i32_e32 v17, v17
	v_mul_f32_e32 v17, v93, v17
	v_mul_f32_e32 v17, 0x3fb8aa3b, v17
	v_exp_f32_e32 v16, v17
	s_waitcnt vmcnt(4)
	v_mfma_f32_16x16x32_f16 v[8:11], v[228:231], v[0:3], 0
	v_mfma_f32_16x16x32_f16 v[8:11], v[232:235], v[4:7], v[8:11]
	global_load_dwordx4 v[228:231], v24, s[70:71]
	global_load_dwordx4 v[232:235], v24, s[70:71] offset:64
	v_add_u32_e32 v24, 0x4000, v24
	s_nop 4
	v_cndmask_b32_e64 v12, v8, v11, s[40:41]
	v_cndmask_b32_e64 v13, v9, v10, s[40:41]
	v_cndmask_b32_e64 v14, v10, v9, s[40:41]
	v_cndmask_b32_e64 v15, v11, v8, s[40:41]
	v_mul_f32_e32 v12, v12, v16
	v_mul_f32_e32 v13, v13, v16
	v_mul_f32_e32 v14, v14, v16
	v_mul_f32_e32 v15, v15, v16
	v_mul_f32_e32 v12, v20, v12
	v_mul_f32_e32 v13, v21, v13
	v_mul_f32_e32 v14, v22, v14
	v_mul_f32_e32 v15, v23, v15
	v_mul_f32_e32 v27, v12, v12
	v_fmac_f32_e32 v27, v13, v13
	v_fmac_f32_e32 v27, v14, v14
	v_fmac_f32_e32 v27, v15, v15
	v_add_f32_e32 v28, v28, v27
	s_mov_b64 exec, s[38:39]
	ds_write_b32 v18, v12
	ds_write_b32 v18, v13 offset:8
	ds_write_b32 v18, v14 offset:16
	ds_write_b32 v18, v15 offset:24
	s_mov_b64 exec, -1
	v_add_u32_e32 v18, v18, v19
	v_add_u32_e32 v17, 0xc80, v25
	v_cvt_f32_i32_e32 v17, v17
	v_mul_f32_e32 v17, v93, v17
	v_mul_f32_e32 v17, 0x3fb8aa3b, v17
	v_exp_f32_e32 v16, v17
	s_waitcnt vmcnt(4)
	v_mfma_f32_16x16x32_f16 v[8:11], v[236:239], v[0:3], 0
	v_mfma_f32_16x16x32_f16 v[8:11], v[240:243], v[4:7], v[8:11]
	global_load_dwordx4 v[236:239], v24, s[70:71]
	global_load_dwordx4 v[240:243], v24, s[70:71] offset:64
	v_add_u32_e32 v24, 0x4000, v24
	s_nop 4
	v_cndmask_b32_e64 v12, v8, v11, s[40:41]
	v_cndmask_b32_e64 v13, v9, v10, s[40:41]
	v_cndmask_b32_e64 v14, v10, v9, s[40:41]
	v_cndmask_b32_e64 v15, v11, v8, s[40:41]
	v_mul_f32_e32 v12, v12, v16
	v_mul_f32_e32 v13, v13, v16
	v_mul_f32_e32 v14, v14, v16
	v_mul_f32_e32 v15, v15, v16
	v_mul_f32_e32 v12, v20, v12
	v_mul_f32_e32 v13, v21, v13
	v_mul_f32_e32 v14, v22, v14
	v_mul_f32_e32 v15, v23, v15
	v_mul_f32_e32 v27, v12, v12
	v_fmac_f32_e32 v27, v13, v13
	v_fmac_f32_e32 v27, v14, v14
	v_fmac_f32_e32 v27, v15, v15
	v_add_f32_e32 v28, v28, v27
	s_mov_b64 exec, s[38:39]
	ds_write_b32 v18, v12
	ds_write_b32 v18, v13 offset:8
	ds_write_b32 v18, v14 offset:16
	ds_write_b32 v18, v15 offset:24
	s_mov_b64 exec, -1
	v_add_u32_e32 v18, v18, v19
	v_add_u32_e32 v17, 0xd00, v25
	v_cvt_f32_i32_e32 v17, v17
	v_mul_f32_e32 v17, v93, v17
	v_mul_f32_e32 v17, 0x3fb8aa3b, v17
	v_exp_f32_e32 v16, v17
	s_waitcnt vmcnt(4)
	v_mfma_f32_16x16x32_f16 v[8:11], v[244:247], v[0:3], 0
	v_mfma_f32_16x16x32_f16 v[8:11], v[248:251], v[4:7], v[8:11]
	global_load_dwordx4 v[244:247], v24, s[70:71]
	global_load_dwordx4 v[248:251], v24, s[70:71] offset:64
	v_add_u32_e32 v24, 0x4000, v24
	s_nop 4
	v_cndmask_b32_e64 v12, v8, v11, s[40:41]
	v_cndmask_b32_e64 v13, v9, v10, s[40:41]
	v_cndmask_b32_e64 v14, v10, v9, s[40:41]
	v_cndmask_b32_e64 v15, v11, v8, s[40:41]
	v_mul_f32_e32 v12, v12, v16
	v_mul_f32_e32 v13, v13, v16
	v_mul_f32_e32 v14, v14, v16
	v_mul_f32_e32 v15, v15, v16
	v_mul_f32_e32 v12, v20, v12
	v_mul_f32_e32 v13, v21, v13
	v_mul_f32_e32 v14, v22, v14
	v_mul_f32_e32 v15, v23, v15
	v_mul_f32_e32 v27, v12, v12
	v_fmac_f32_e32 v27, v13, v13
	v_fmac_f32_e32 v27, v14, v14
	v_fmac_f32_e32 v27, v15, v15
	v_add_f32_e32 v28, v28, v27
	s_mov_b64 exec, s[38:39]
	ds_write_b32 v18, v12
	ds_write_b32 v18, v13 offset:8
	ds_write_b32 v18, v14 offset:16
	ds_write_b32 v18, v15 offset:24
	s_mov_b64 exec, -1
	v_add_u32_e32 v18, v18, v19
	v_add_u32_e32 v17, 0xd80, v25
	v_cvt_f32_i32_e32 v17, v17
	v_mul_f32_e32 v17, v93, v17
	v_mul_f32_e32 v17, 0x3fb8aa3b, v17
	v_exp_f32_e32 v16, v17
	s_waitcnt vmcnt(4)
	v_mfma_f32_16x16x32_f16 v[8:11], v[228:231], v[0:3], 0
	v_mfma_f32_16x16x32_f16 v[8:11], v[232:235], v[4:7], v[8:11]
	global_load_dwordx4 v[228:231], v24, s[70:71]
	global_load_dwordx4 v[232:235], v24, s[70:71] offset:64
	v_add_u32_e32 v24, 0x4000, v24
	s_nop 4
	v_cndmask_b32_e64 v12, v8, v11, s[40:41]
	v_cndmask_b32_e64 v13, v9, v10, s[40:41]
	v_cndmask_b32_e64 v14, v10, v9, s[40:41]
	v_cndmask_b32_e64 v15, v11, v8, s[40:41]
	v_mul_f32_e32 v12, v12, v16
	v_mul_f32_e32 v13, v13, v16
	v_mul_f32_e32 v14, v14, v16
	v_mul_f32_e32 v15, v15, v16
	v_mul_f32_e32 v12, v20, v12
	v_mul_f32_e32 v13, v21, v13
	v_mul_f32_e32 v14, v22, v14
	v_mul_f32_e32 v15, v23, v15
	v_mul_f32_e32 v27, v12, v12
	v_fmac_f32_e32 v27, v13, v13
	v_fmac_f32_e32 v27, v14, v14
	v_fmac_f32_e32 v27, v15, v15
	v_add_f32_e32 v28, v28, v27
	s_mov_b64 exec, s[38:39]
	ds_write_b32 v18, v12
	ds_write_b32 v18, v13 offset:8
	ds_write_b32 v18, v14 offset:16
	ds_write_b32 v18, v15 offset:24
	s_mov_b64 exec, -1
	v_add_u32_e32 v18, v18, v19
	v_add_u32_e32 v17, 0xe00, v25
	v_cvt_f32_i32_e32 v17, v17
	v_mul_f32_e32 v17, v93, v17
	v_mul_f32_e32 v17, 0x3fb8aa3b, v17
	v_exp_f32_e32 v16, v17
	s_waitcnt vmcnt(4)
; __device__ __forceinline__ void phase_hyena(KP kp_, int hf){ asm volatile("" : "+s"(kp_)); const Params p=load_params(kp_);
;     ...
;       _Pragma("unroll 8") for (int i=0;i<64;++i){ int tl=wid+8*i;
;         const _Float16* ap=a3+(size_t)(tl*16+n)*64+kg*8;
;         f16x8 a0=*(const f16x8*)ap, a1=*(const f16x8*)(ap+32);
;         f32x4 dd={0.f,0.f,0.f,0.f};
;         dd=__builtin_amdgcn_mfma_f32_16x16x32_f16(a0,bw0,dd,0,0,0);
;         dd=__builtin_amdgcn_mfma_f32_16x16x32_f16(a1,bw1,dd,0,0,0);
;         if (n<4){ float d0=__expf(dsc*(float)(tl*16)); int lag0=tl*16+kg*4;
;           float v0=dd[0]*d0*pj0, v1=dd[1]*d0*pj1, v2=dd[2]*d0*pj2, v3=dd[3]*d0*pj3;
;           if (!side1){ Zf[2*(lag0)+order]=v0; Zf[2*(lag0+1)+order]=v1; Zf[2*(lag0+2)+order]=v2; Zf[2*(lag0+3)+order]=v3; ssl+=v0*v0+v1*v1+v2*v2+v3*v3; }
;           else { if (lag0>=1){ Zf[2*(16384-lag0)+order]=v0; ssl+=v0*v0; }
;             Zf[2*(16384-lag0-1)+order]=v1; Zf[2*(16384-lag0-2)+order]=v2; Zf[2*(16384-lag0-3)+order]=v3; ssl+=v1*v1+v2*v2+v3*v3; } }
	v_mfma_f32_16x16x32_f16 v[8:11], v[236:239], v[0:3], 0
	v_mfma_f32_16x16x32_f16 v[8:11], v[240:243], v[4:7], v[8:11]
	global_load_dwordx4 v[236:239], v24, s[70:71]
	global_load_dwordx4 v[240:243], v24, s[70:71] offset:64
	v_add_u32_e32 v24, 0x4000, v24
	s_nop 4
	v_cndmask_b32_e64 v12, v8, v11, s[40:41]
	v_cndmask_b32_e64 v13, v9, v10, s[40:41]
	v_cndmask_b32_e64 v14, v10, v9, s[40:41]
	v_cndmask_b32_e64 v15, v11, v8, s[40:41]
	v_mul_f32_e32 v12, v12, v16
	v_mul_f32_e32 v13, v13, v16
	v_mul_f32_e32 v14, v14, v16
	v_mul_f32_e32 v15, v15, v16
	v_mul_f32_e32 v12, v20, v12
	v_mul_f32_e32 v13, v21, v13
	v_mul_f32_e32 v14, v22, v14
	v_mul_f32_e32 v15, v23, v15
	v_mul_f32_e32 v27, v12, v12
	v_fmac_f32_e32 v27, v13, v13
	v_fmac_f32_e32 v27, v14, v14
	v_fmac_f32_e32 v27, v15, v15
	v_add_f32_e32 v28, v28, v27
	s_mov_b64 exec, s[38:39]
	ds_write_b32 v18, v12
	ds_write_b32 v18, v13 offset:8
	ds_write_b32 v18, v14 offset:16
	ds_write_b32 v18, v15 offset:24
	s_mov_b64 exec, -1
	v_add_u32_e32 v18, v18, v19
	v_add_u32_e32 v17, 0xe80, v25
	v_cvt_f32_i32_e32 v17, v17
	v_mul_f32_e32 v17, v93, v17
	v_mul_f32_e32 v17, 0x3fb8aa3b, v17
	v_exp_f32_e32 v16, v17
	s_waitcnt vmcnt(4)
	v_mfma_f32_16x16x32_f16 v[8:11], v[244:247], v[0:3], 0
	v_mfma_f32_16x16x32_f16 v[8:11], v[248:251], v[4:7], v[8:11]
	global_load_dwordx4 v[244:247], v24, s[70:71]
	global_load_dwordx4 v[248:251], v24, s[70:71] offset:64
	v_add_u32_e32 v24, 0x4000, v24
	s_nop 4
	v_cndmask_b32_e64 v12, v8, v11, s[40:41]
	v_cndmask_b32_e64 v13, v9, v10, s[40:41]
	v_cndmask_b32_e64 v14, v10, v9, s[40:41]
	v_cndmask_b32_e64 v15, v11, v8, s[40:41]
	v_mul_f32_e32 v12, v12, v16
	v_mul_f32_e32 v13, v13, v16
	v_mul_f32_e32 v14, v14, v16
	v_mul_f32_e32 v15, v15, v16
	v_mul_f32_e32 v12, v20, v12
	v_mul_f32_e32 v13, v21, v13
	v_mul_f32_e32 v14, v22, v14
	v_mul_f32_e32 v15, v23, v15
	v_mul_f32_e32 v27, v12, v12
	v_fmac_f32_e32 v27, v13, v13
	v_fmac_f32_e32 v27, v14, v14
	v_fmac_f32_e32 v27, v15, v15
	v_add_f32_e32 v28, v28, v27
	s_mov_b64 exec, s[38:39]
	ds_write_b32 v18, v12
	ds_write_b32 v18, v13 offset:8
	ds_write_b32 v18, v14 offset:16
	ds_write_b32 v18, v15 offset:24
	s_mov_b64 exec, -1
	v_add_u32_e32 v18, v18, v19
	v_add_u32_e32 v17, 0xf00, v25
	v_cvt_f32_i32_e32 v17, v17
	v_mul_f32_e32 v17, v93, v17
	v_mul_f32_e32 v17, 0x3fb8aa3b, v17
	v_exp_f32_e32 v16, v17
	s_waitcnt vmcnt(4)
	v_mfma_f32_16x16x32_f16 v[8:11], v[228:231], v[0:3], 0
	v_mfma_f32_16x16x32_f16 v[8:11], v[232:235], v[4:7], v[8:11]
	global_load_dwordx4 v[228:231], v24, s[70:71]
	global_load_dwordx4 v[232:235], v24, s[70:71] offset:64
	v_add_u32_e32 v24, 0x4000, v24
	s_nop 4
	v_cndmask_b32_e64 v12, v8, v11, s[40:41]
	v_cndmask_b32_e64 v13, v9, v10, s[40:41]
	v_cndmask_b32_e64 v14, v10, v9, s[40:41]
	v_cndmask_b32_e64 v15, v11, v8, s[40:41]
	v_mul_f32_e32 v12, v12, v16
	v_mul_f32_e32 v13, v13, v16
	v_mul_f32_e32 v14, v14, v16
	v_mul_f32_e32 v15, v15, v16
	v_mul_f32_e32 v12, v20, v12
	v_mul_f32_e32 v13, v21, v13
	v_mul_f32_e32 v14, v22, v14
	v_mul_f32_e32 v15, v23, v15
	v_mul_f32_e32 v27, v12, v12
	v_fmac_f32_e32 v27, v13, v13
	v_fmac_f32_e32 v27, v14, v14
	v_fmac_f32_e32 v27, v15, v15
	v_add_f32_e32 v28, v28, v27
	s_mov_b64 exec, s[38:39]
	ds_write_b32 v18, v12
	ds_write_b32 v18, v13 offset:8
	ds_write_b32 v18, v14 offset:16
	ds_write_b32 v18, v15 offset:24
	s_mov_b64 exec, -1
	v_add_u32_e32 v18, v18, v19
	v_add_u32_e32 v17, 0xf80, v25
	v_cvt_f32_i32_e32 v17, v17
	v_mul_f32_e32 v17, v93, v17
	v_mul_f32_e32 v17, 0x3fb8aa3b, v17
	v_exp_f32_e32 v16, v17
	s_waitcnt vmcnt(4)
	v_mfma_f32_16x16x32_f16 v[8:11], v[236:239], v[0:3], 0
	v_mfma_f32_16x16x32_f16 v[8:11], v[240:243], v[4:7], v[8:11]
	global_load_dwordx4 v[236:239], v24, s[70:71]
	global_load_dwordx4 v[240:243], v24, s[70:71] offset:64
	v_add_u32_e32 v24, 0x4000, v24
	s_nop 4
	v_cndmask_b32_e64 v12, v8, v11, s[40:41]
	v_cndmask_b32_e64 v13, v9, v10, s[40:41]
	v_cndmask_b32_e64 v14, v10, v9, s[40:41]
	v_cndmask_b32_e64 v15, v11, v8, s[40:41]
	v_mul_f32_e32 v12, v12, v16
	v_mul_f32_e32 v13, v13, v16
	v_mul_f32_e32 v14, v14, v16
	v_mul_f32_e32 v15, v15, v16
	v_mul_f32_e32 v12, v20, v12
	v_mul_f32_e32 v13, v21, v13
	v_mul_f32_e32 v14, v22, v14
	v_mul_f32_e32 v15, v23, v15
	v_mul_f32_e32 v27, v12, v12
	v_fmac_f32_e32 v27, v13, v13
	v_fmac_f32_e32 v27, v14, v14
	v_fmac_f32_e32 v27, v15, v15
	v_add_f32_e32 v28, v28, v27
	s_mov_b64 exec, s[38:39]
	ds_write_b32 v18, v12
	ds_write_b32 v18, v13 offset:8
	ds_write_b32 v18, v14 offset:16
	ds_write_b32 v18, v15 offset:24
	s_mov_b64 exec, -1
	v_add_u32_e32 v18, v18, v19
	v_add_u32_e32 v17, 0x1000, v25
	v_cvt_f32_i32_e32 v17, v17
	v_mul_f32_e32 v17, v93, v17
	v_mul_f32_e32 v17, 0x3fb8aa3b, v17
	v_exp_f32_e32 v16, v17
	s_waitcnt vmcnt(4)
	v_mfma_f32_16x16x32_f16 v[8:11], v[244:247], v[0:3], 0
	v_mfma_f32_16x16x32_f16 v[8:11], v[248:251], v[4:7], v[8:11]
	global_load_dwordx4 v[244:247], v24, s[70:71]
	global_load_dwordx4 v[248:251], v24, s[70:71] offset:64
	v_add_u32_e32 v24, 0x4000, v24
	s_nop 4
	v_cndmask_b32_e64 v12, v8, v11, s[40:41]
	v_cndmask_b32_e64 v13, v9, v10, s[40:41]
	v_cndmask_b32_e64 v14, v10, v9, s[40:41]
	v_cndmask_b32_e64 v15, v11, v8, s[40:41]
	v_mul_f32_e32 v12, v12, v16
	v_mul_f32_e32 v13, v13, v16
	v_mul_f32_e32 v14, v14, v16
	v_mul_f32_e32 v15, v15, v16
	v_mul_f32_e32 v12, v20, v12
	v_mul_f32_e32 v13, v21, v13
	v_mul_f32_e32 v14, v22, v14
	v_mul_f32_e32 v15, v23, v15
	v_mul_f32_e32 v27, v12, v12
	v_fmac_f32_e32 v27, v13, v13
	v_fmac_f32_e32 v27, v14, v14
	v_fmac_f32_e32 v27, v15, v15
	v_add_f32_e32 v28, v28, v27
	s_mov_b64 exec, s[38:39]
	ds_write_b32 v18, v12
	ds_write_b32 v18, v13 offset:8
	ds_write_b32 v18, v14 offset:16
	ds_write_b32 v18, v15 offset:24
	s_mov_b64 exec, -1
	v_add_u32_e32 v18, v18, v19
	v_add_u32_e32 v17, 0x1080, v25
	v_cvt_f32_i32_e32 v17, v17
	v_mul_f32_e32 v17, v93, v17
	v_mul_f32_e32 v17, 0x3fb8aa3b, v17
	v_exp_f32_e32 v16, v17
	s_waitcnt vmcnt(4)
; __device__ __forceinline__ void phase_hyena(KP kp_, int hf){ asm volatile("" : "+s"(kp_)); const Params p=load_params(kp_);
;     ...
;       _Pragma("unroll 8") for (int i=0;i<64;++i){ int tl=wid+8*i;
;         const _Float16* ap=a3+(size_t)(tl*16+n)*64+kg*8;
;         f16x8 a0=*(const f16x8*)ap, a1=*(const f16x8*)(ap+32);
;         f32x4 dd={0.f,0.f,0.f,0.f};
;         dd=__builtin_amdgcn_mfma_f32_16x16x32_f16(a0,bw0,dd,0,0,0);
;         dd=__builtin_amdgcn_mfma_f32_16x16x32_f16(a1,bw1,dd,0,0,0);
;         if (n<4){ float d0=__expf(dsc*(float)(tl*16)); int lag0=tl*16+kg*4;
;           float v0=dd[0]*d0*pj0, v1=dd[1]*d0*pj1, v2=dd[2]*d0*pj2, v3=dd[3]*d0*pj3;
;           if (!side1){ Zf[2*(lag0)+order]=v0; Zf[2*(lag0+1)+order]=v1; Zf[2*(lag0+2)+order]=v2; Zf[2*(lag0+3)+order]=v3; ssl+=v0*v0+v1*v1+v2*v2+v3*v3; }
;           else { if (lag0>=1){ Zf[2*(16384-lag0)+order]=v0; ssl+=v0*v0; }
;             Zf[2*(16384-lag0-1)+order]=v1; Zf[2*(16384-lag0-2)+order]=v2; Zf[2*(16384-lag0-3)+order]=v3; ssl+=v1*v1+v2*v2+v3*v3; } }
	v_mfma_f32_16x16x32_f16 v[8:11], v[228:231], v[0:3], 0
	v_mfma_f32_16x16x32_f16 v[8:11], v[232:235], v[4:7], v[8:11]
	global_load_dwordx4 v[228:231], v24, s[70:71]
	global_load_dwordx4 v[232:235], v24, s[70:71] offset:64
	v_add_u32_e32 v24, 0x4000, v24
	s_nop 4
	v_cndmask_b32_e64 v12, v8, v11, s[40:41]
	v_cndmask_b32_e64 v13, v9, v10, s[40:41]
	v_cndmask_b32_e64 v14, v10, v9, s[40:41]
	v_cndmask_b32_e64 v15, v11, v8, s[40:41]
	v_mul_f32_e32 v12, v12, v16
	v_mul_f32_e32 v13, v13, v16
	v_mul_f32_e32 v14, v14, v16
	v_mul_f32_e32 v15, v15, v16
	v_mul_f32_e32 v12, v20, v12
	v_mul_f32_e32 v13, v21, v13
	v_mul_f32_e32 v14, v22, v14
	v_mul_f32_e32 v15, v23, v15
	v_mul_f32_e32 v27, v12, v12
	v_fmac_f32_e32 v27, v13, v13
	v_fmac_f32_e32 v27, v14, v14
	v_fmac_f32_e32 v27, v15, v15
	v_add_f32_e32 v28, v28, v27
	s_mov_b64 exec, s[38:39]
	ds_write_b32 v18, v12
	ds_write_b32 v18, v13 offset:8
	ds_write_b32 v18, v14 offset:16
	ds_write_b32 v18, v15 offset:24
	s_mov_b64 exec, -1
	v_add_u32_e32 v18, v18, v19
	v_add_u32_e32 v17, 0x1100, v25
	v_cvt_f32_i32_e32 v17, v17
	v_mul_f32_e32 v17, v93, v17
	v_mul_f32_e32 v17, 0x3fb8aa3b, v17
	v_exp_f32_e32 v16, v17
	s_waitcnt vmcnt(4)
	v_mfma_f32_16x16x32_f16 v[8:11], v[236:239], v[0:3], 0
	v_mfma_f32_16x16x32_f16 v[8:11], v[240:243], v[4:7], v[8:11]
	global_load_dwordx4 v[236:239], v24, s[70:71]
	global_load_dwordx4 v[240:243], v24, s[70:71] offset:64
	v_add_u32_e32 v24, 0x4000, v24
	s_nop 4
	v_cndmask_b32_e64 v12, v8, v11, s[40:41]
	v_cndmask_b32_e64 v13, v9, v10, s[40:41]
	v_cndmask_b32_e64 v14, v10, v9, s[40:41]
	v_cndmask_b32_e64 v15, v11, v8, s[40:41]
	v_mul_f32_e32 v12, v12, v16
	v_mul_f32_e32 v13, v13, v16
	v_mul_f32_e32 v14, v14, v16
	v_mul_f32_e32 v15, v15, v16
	v_mul_f32_e32 v12, v20, v12
	v_mul_f32_e32 v13, v21, v13
	v_mul_f32_e32 v14, v22, v14
	v_mul_f32_e32 v15, v23, v15
	v_mul_f32_e32 v27, v12, v12
	v_fmac_f32_e32 v27, v13, v13
	v_fmac_f32_e32 v27, v14, v14
	v_fmac_f32_e32 v27, v15, v15
	v_add_f32_e32 v28, v28, v27
	s_mov_b64 exec, s[38:39]
	ds_write_b32 v18, v12
	ds_write_b32 v18, v13 offset:8
	ds_write_b32 v18, v14 offset:16
	ds_write_b32 v18, v15 offset:24
	s_mov_b64 exec, -1
	v_add_u32_e32 v18, v18, v19
	v_add_u32_e32 v17, 0x1180, v25
	v_cvt_f32_i32_e32 v17, v17
	v_mul_f32_e32 v17, v93, v17
	v_mul_f32_e32 v17, 0x3fb8aa3b, v17
	v_exp_f32_e32 v16, v17
	s_waitcnt vmcnt(4)
	v_mfma_f32_16x16x32_f16 v[8:11], v[244:247], v[0:3], 0
	v_mfma_f32_16x16x32_f16 v[8:11], v[248:251], v[4:7], v[8:11]
	global_load_dwordx4 v[244:247], v24, s[70:71]
	global_load_dwordx4 v[248:251], v24, s[70:71] offset:64
	v_add_u32_e32 v24, 0x4000, v24
	s_nop 4
	v_cndmask_b32_e64 v12, v8, v11, s[40:41]
	v_cndmask_b32_e64 v13, v9, v10, s[40:41]
	v_cndmask_b32_e64 v14, v10, v9, s[40:41]
	v_cndmask_b32_e64 v15, v11, v8, s[40:41]
	v_mul_f32_e32 v12, v12, v16
	v_mul_f32_e32 v13, v13, v16
	v_mul_f32_e32 v14, v14, v16
	v_mul_f32_e32 v15, v15, v16
	v_mul_f32_e32 v12, v20, v12
	v_mul_f32_e32 v13, v21, v13
	v_mul_f32_e32 v14, v22, v14
	v_mul_f32_e32 v15, v23, v15
	v_mul_f32_e32 v27, v12, v12
	v_fmac_f32_e32 v27, v13, v13
	v_fmac_f32_e32 v27, v14, v14
	v_fmac_f32_e32 v27, v15, v15
	v_add_f32_e32 v28, v28, v27
	s_mov_b64 exec, s[38:39]
	ds_write_b32 v18, v12
	ds_write_b32 v18, v13 offset:8
	ds_write_b32 v18, v14 offset:16
	ds_write_b32 v18, v15 offset:24
	s_mov_b64 exec, -1
	v_add_u32_e32 v18, v18, v19
	v_add_u32_e32 v17, 0x1200, v25
	v_cvt_f32_i32_e32 v17, v17
	v_mul_f32_e32 v17, v93, v17
	v_mul_f32_e32 v17, 0x3fb8aa3b, v17
	v_exp_f32_e32 v16, v17
	s_waitcnt vmcnt(4)
	v_mfma_f32_16x16x32_f16 v[8:11], v[228:231], v[0:3], 0
	v_mfma_f32_16x16x32_f16 v[8:11], v[232:235], v[4:7], v[8:11]
	global_load_dwordx4 v[228:231], v24, s[70:71]
	global_load_dwordx4 v[232:235], v24, s[70:71] offset:64
	v_add_u32_e32 v24, 0x4000, v24
	s_nop 4
	v_cndmask_b32_e64 v12, v8, v11, s[40:41]
	v_cndmask_b32_e64 v13, v9, v10, s[40:41]
	v_cndmask_b32_e64 v14, v10, v9, s[40:41]
	v_cndmask_b32_e64 v15, v11, v8, s[40:41]
	v_mul_f32_e32 v12, v12, v16
	v_mul_f32_e32 v13, v13, v16
	v_mul_f32_e32 v14, v14, v16
	v_mul_f32_e32 v15, v15, v16
	v_mul_f32_e32 v12, v20, v12
	v_mul_f32_e32 v13, v21, v13
	v_mul_f32_e32 v14, v22, v14
	v_mul_f32_e32 v15, v23, v15
	v_mul_f32_e32 v27, v12, v12
	v_fmac_f32_e32 v27, v13, v13
	v_fmac_f32_e32 v27, v14, v14
	v_fmac_f32_e32 v27, v15, v15
	v_add_f32_e32 v28, v28, v27
	s_mov_b64 exec, s[38:39]
	ds_write_b32 v18, v12
	ds_write_b32 v18, v13 offset:8
	ds_write_b32 v18, v14 offset:16
	ds_write_b32 v18, v15 offset:24
	s_mov_b64 exec, -1
	v_add_u32_e32 v18, v18, v19
	v_add_u32_e32 v17, 0x1280, v25
	v_cvt_f32_i32_e32 v17, v17
	v_mul_f32_e32 v17, v93, v17
	v_mul_f32_e32 v17, 0x3fb8aa3b, v17
	v_exp_f32_e32 v16, v17
	s_waitcnt vmcnt(4)
	v_mfma_f32_16x16x32_f16 v[8:11], v[236:239], v[0:3], 0
	v_mfma_f32_16x16x32_f16 v[8:11], v[240:243], v[4:7], v[8:11]
	global_load_dwordx4 v[236:239], v24, s[70:71]
	global_load_dwordx4 v[240:243], v24, s[70:71] offset:64
	v_add_u32_e32 v24, 0x4000, v24
	s_nop 4
	v_cndmask_b32_e64 v12, v8, v11, s[40:41]
	v_cndmask_b32_e64 v13, v9, v10, s[40:41]
	v_cndmask_b32_e64 v14, v10, v9, s[40:41]
	v_cndmask_b32_e64 v15, v11, v8, s[40:41]
	v_mul_f32_e32 v12, v12, v16
	v_mul_f32_e32 v13, v13, v16
	v_mul_f32_e32 v14, v14, v16
	v_mul_f32_e32 v15, v15, v16
	v_mul_f32_e32 v12, v20, v12
	v_mul_f32_e32 v13, v21, v13
	v_mul_f32_e32 v14, v22, v14
	v_mul_f32_e32 v15, v23, v15
	v_mul_f32_e32 v27, v12, v12
	v_fmac_f32_e32 v27, v13, v13
	v_fmac_f32_e32 v27, v14, v14
	v_fmac_f32_e32 v27, v15, v15
	v_add_f32_e32 v28, v28, v27
	s_mov_b64 exec, s[38:39]
	ds_write_b32 v18, v12
	ds_write_b32 v18, v13 offset:8
	ds_write_b32 v18, v14 offset:16
	ds_write_b32 v18, v15 offset:24
	s_mov_b64 exec, -1
	v_add_u32_e32 v18, v18, v19
	v_add_u32_e32 v17, 0x1300, v25
	v_cvt_f32_i32_e32 v17, v17
	v_mul_f32_e32 v17, v93, v17
	v_mul_f32_e32 v17, 0x3fb8aa3b, v17
	v_exp_f32_e32 v16, v17
	s_waitcnt vmcnt(4)
; __device__ __forceinline__ void phase_hyena(KP kp_, int hf){ asm volatile("" : "+s"(kp_)); const Params p=load_params(kp_);
;     ...
;       _Pragma("unroll 8") for (int i=0;i<64;++i){ int tl=wid+8*i;
;         const _Float16* ap=a3+(size_t)(tl*16+n)*64+kg*8;
;         f16x8 a0=*(const f16x8*)ap, a1=*(const f16x8*)(ap+32);
;         f32x4 dd={0.f,0.f,0.f,0.f};
;         dd=__builtin_amdgcn_mfma_f32_16x16x32_f16(a0,bw0,dd,0,0,0);
;         dd=__builtin_amdgcn_mfma_f32_16x16x32_f16(a1,bw1,dd,0,0,0);
;         if (n<4){ float d0=__expf(dsc*(float)(tl*16)); int lag0=tl*16+kg*4;
;           float v0=dd[0]*d0*pj0, v1=dd[1]*d0*pj1, v2=dd[2]*d0*pj2, v3=dd[3]*d0*pj3;
;           if (!side1){ Zf[2*(lag0)+order]=v0; Zf[2*(lag0+1)+order]=v1; Zf[2*(lag0+2)+order]=v2; Zf[2*(lag0+3)+order]=v3; ssl+=v0*v0+v1*v1+v2*v2+v3*v3; }
;           else { if (lag0>=1){ Zf[2*(16384-lag0)+order]=v0; ssl+=v0*v0; }
;             Zf[2*(16384-lag0-1)+order]=v1; Zf[2*(16384-lag0-2)+order]=v2; Zf[2*(16384-lag0-3)+order]=v3; ssl+=v1*v1+v2*v2+v3*v3; } }
	v_mfma_f32_16x16x32_f16 v[8:11], v[244:247], v[0:3], 0
	v_mfma_f32_16x16x32_f16 v[8:11], v[248:251], v[4:7], v[8:11]
	global_load_dwordx4 v[244:247], v24, s[70:71]
	global_load_dwordx4 v[248:251], v24, s[70:71] offset:64
	v_add_u32_e32 v24, 0x4000, v24
	s_nop 4
	v_cndmask_b32_e64 v12, v8, v11, s[40:41]
	v_cndmask_b32_e64 v13, v9, v10, s[40:41]
	v_cndmask_b32_e64 v14, v10, v9, s[40:41]
	v_cndmask_b32_e64 v15, v11, v8, s[40:41]
	v_mul_f32_e32 v12, v12, v16
	v_mul_f32_e32 v13, v13, v16
	v_mul_f32_e32 v14, v14, v16
	v_mul_f32_e32 v15, v15, v16
	v_mul_f32_e32 v12, v20, v12
	v_mul_f32_e32 v13, v21, v13
	v_mul_f32_e32 v14, v22, v14
	v_mul_f32_e32 v15, v23, v15
	v_mul_f32_e32 v27, v12, v12
	v_fmac_f32_e32 v27, v13, v13
	v_fmac_f32_e32 v27, v14, v14
	v_fmac_f32_e32 v27, v15, v15
	v_add_f32_e32 v28, v28, v27
	s_mov_b64 exec, s[38:39]
	ds_write_b32 v18, v12
	ds_write_b32 v18, v13 offset:8
	ds_write_b32 v18, v14 offset:16
	ds_write_b32 v18, v15 offset:24
	s_mov_b64 exec, -1
	v_add_u32_e32 v18, v18, v19
	v_add_u32_e32 v17, 0x1380, v25
	v_cvt_f32_i32_e32 v17, v17
	v_mul_f32_e32 v17, v93, v17
	v_mul_f32_e32 v17, 0x3fb8aa3b, v17
	v_exp_f32_e32 v16, v17
	s_waitcnt vmcnt(4)
	v_mfma_f32_16x16x32_f16 v[8:11], v[228:231], v[0:3], 0
	v_mfma_f32_16x16x32_f16 v[8:11], v[232:235], v[4:7], v[8:11]
	global_load_dwordx4 v[228:231], v24, s[70:71]
	global_load_dwordx4 v[232:235], v24, s[70:71] offset:64
	v_add_u32_e32 v24, 0x4000, v24
	s_nop 4
	v_cndmask_b32_e64 v12, v8, v11, s[40:41]
	v_cndmask_b32_e64 v13, v9, v10, s[40:41]
	v_cndmask_b32_e64 v14, v10, v9, s[40:41]
	v_cndmask_b32_e64 v15, v11, v8, s[40:41]
	v_mul_f32_e32 v12, v12, v16
	v_mul_f32_e32 v13, v13, v16
	v_mul_f32_e32 v14, v14, v16
	v_mul_f32_e32 v15, v15, v16
	v_mul_f32_e32 v12, v20, v12
	v_mul_f32_e32 v13, v21, v13
	v_mul_f32_e32 v14, v22, v14
	v_mul_f32_e32 v15, v23, v15
	v_mul_f32_e32 v27, v12, v12
	v_fmac_f32_e32 v27, v13, v13
	v_fmac_f32_e32 v27, v14, v14
	v_fmac_f32_e32 v27, v15, v15
	v_add_f32_e32 v28, v28, v27
	s_mov_b64 exec, s[38:39]
	ds_write_b32 v18, v12
	ds_write_b32 v18, v13 offset:8
	ds_write_b32 v18, v14 offset:16
	ds_write_b32 v18, v15 offset:24
	s_mov_b64 exec, -1
	v_add_u32_e32 v18, v18, v19
	v_add_u32_e32 v17, 0x1400, v25
	v_cvt_f32_i32_e32 v17, v17
	v_mul_f32_e32 v17, v93, v17
	v_mul_f32_e32 v17, 0x3fb8aa3b, v17
	v_exp_f32_e32 v16, v17
	s_waitcnt vmcnt(4)
	v_mfma_f32_16x16x32_f16 v[8:11], v[236:239], v[0:3], 0
	v_mfma_f32_16x16x32_f16 v[8:11], v[240:243], v[4:7], v[8:11]
	global_load_dwordx4 v[236:239], v24, s[70:71]
	global_load_dwordx4 v[240:243], v24, s[70:71] offset:64
	v_add_u32_e32 v24, 0x4000, v24
	s_nop 4
	v_cndmask_b32_e64 v12, v8, v11, s[40:41]
	v_cndmask_b32_e64 v13, v9, v10, s[40:41]
	v_cndmask_b32_e64 v14, v10, v9, s[40:41]
	v_cndmask_b32_e64 v15, v11, v8, s[40:41]
	v_mul_f32_e32 v12, v12, v16
	v_mul_f32_e32 v13, v13, v16
	v_mul_f32_e32 v14, v14, v16
	v_mul_f32_e32 v15, v15, v16
	v_mul_f32_e32 v12, v20, v12
	v_mul_f32_e32 v13, v21, v13
	v_mul_f32_e32 v14, v22, v14
	v_mul_f32_e32 v15, v23, v15
	v_mul_f32_e32 v27, v12, v12
	v_fmac_f32_e32 v27, v13, v13
	v_fmac_f32_e32 v27, v14, v14
	v_fmac_f32_e32 v27, v15, v15
	v_add_f32_e32 v28, v28, v27
	s_mov_b64 exec, s[38:39]
	ds_write_b32 v18, v12
	ds_write_b32 v18, v13 offset:8
	ds_write_b32 v18, v14 offset:16
	ds_write_b32 v18, v15 offset:24
	s_mov_b64 exec, -1
	v_add_u32_e32 v18, v18, v19
	v_add_u32_e32 v17, 0x1480, v25
	v_cvt_f32_i32_e32 v17, v17
	v_mul_f32_e32 v17, v93, v17
	v_mul_f32_e32 v17, 0x3fb8aa3b, v17
	v_exp_f32_e32 v16, v17
	s_waitcnt vmcnt(4)
	v_mfma_f32_16x16x32_f16 v[8:11], v[244:247], v[0:3], 0
	v_mfma_f32_16x16x32_f16 v[8:11], v[248:251], v[4:7], v[8:11]
	global_load_dwordx4 v[244:247], v24, s[70:71]
	global_load_dwordx4 v[248:251], v24, s[70:71] offset:64
	v_add_u32_e32 v24, 0x4000, v24
	s_nop 4
	v_cndmask_b32_e64 v12, v8, v11, s[40:41]
	v_cndmask_b32_e64 v13, v9, v10, s[40:41]
	v_cndmask_b32_e64 v14, v10, v9, s[40:41]
	v_cndmask_b32_e64 v15, v11, v8, s[40:41]
	v_mul_f32_e32 v12, v12, v16
	v_mul_f32_e32 v13, v13, v16
	v_mul_f32_e32 v14, v14, v16
	v_mul_f32_e32 v15, v15, v16
	v_mul_f32_e32 v12, v20, v12
	v_mul_f32_e32 v13, v21, v13
	v_mul_f32_e32 v14, v22, v14
	v_mul_f32_e32 v15, v23, v15
	v_mul_f32_e32 v27, v12, v12
	v_fmac_f32_e32 v27, v13, v13
	v_fmac_f32_e32 v27, v14, v14
	v_fmac_f32_e32 v27, v15, v15
	v_add_f32_e32 v28, v28, v27
	s_mov_b64 exec, s[38:39]
	ds_write_b32 v18, v12
	ds_write_b32 v18, v13 offset:8
	ds_write_b32 v18, v14 offset:16
	ds_write_b32 v18, v15 offset:24
	s_mov_b64 exec, -1
	v_add_u32_e32 v18, v18, v19
	v_add_u32_e32 v17, 0x1500, v25
	v_cvt_f32_i32_e32 v17, v17
	v_mul_f32_e32 v17, v93, v17
	v_mul_f32_e32 v17, 0x3fb8aa3b, v17
	v_exp_f32_e32 v16, v17
	s_waitcnt vmcnt(4)
	v_mfma_f32_16x16x32_f16 v[8:11], v[228:231], v[0:3], 0
	v_mfma_f32_16x16x32_f16 v[8:11], v[232:235], v[4:7], v[8:11]
	global_load_dwordx4 v[228:231], v24, s[70:71]
	global_load_dwordx4 v[232:235], v24, s[70:71] offset:64
	v_add_u32_e32 v24, 0x4000, v24
	s_nop 4
	v_cndmask_b32_e64 v12, v8, v11, s[40:41]
	v_cndmask_b32_e64 v13, v9, v10, s[40:41]
	v_cndmask_b32_e64 v14, v10, v9, s[40:41]
	v_cndmask_b32_e64 v15, v11, v8, s[40:41]
	v_mul_f32_e32 v12, v12, v16
	v_mul_f32_e32 v13, v13, v16
	v_mul_f32_e32 v14, v14, v16
	v_mul_f32_e32 v15, v15, v16
	v_mul_f32_e32 v12, v20, v12
	v_mul_f32_e32 v13, v21, v13
	v_mul_f32_e32 v14, v22, v14
	v_mul_f32_e32 v15, v23, v15
	v_mul_f32_e32 v27, v12, v12
	v_fmac_f32_e32 v27, v13, v13
	v_fmac_f32_e32 v27, v14, v14
	v_fmac_f32_e32 v27, v15, v15
	v_add_f32_e32 v28, v28, v27
	s_mov_b64 exec, s[38:39]
	ds_write_b32 v18, v12
	ds_write_b32 v18, v13 offset:8
	ds_write_b32 v18, v14 offset:16
	ds_write_b32 v18, v15 offset:24
	s_mov_b64 exec, -1
	v_add_u32_e32 v18, v18, v19
	v_add_u32_e32 v17, 0x1580, v25
	v_cvt_f32_i32_e32 v17, v17
	v_mul_f32_e32 v17, v93, v17
	v_mul_f32_e32 v17, 0x3fb8aa3b, v17
	v_exp_f32_e32 v16, v17
	s_waitcnt vmcnt(4)
; __device__ __forceinline__ void phase_hyena(KP kp_, int hf){ asm volatile("" : "+s"(kp_)); const Params p=load_params(kp_);
;     ...
;       _Pragma("unroll 8") for (int i=0;i<64;++i){ int tl=wid+8*i;
;         const _Float16* ap=a3+(size_t)(tl*16+n)*64+kg*8;
;         f16x8 a0=*(const f16x8*)ap, a1=*(const f16x8*)(ap+32);
;         f32x4 dd={0.f,0.f,0.f,0.f};
;         dd=__builtin_amdgcn_mfma_f32_16x16x32_f16(a0,bw0,dd,0,0,0);
;         dd=__builtin_amdgcn_mfma_f32_16x16x32_f16(a1,bw1,dd,0,0,0);
;         if (n<4){ float d0=__expf(dsc*(float)(tl*16)); int lag0=tl*16+kg*4;
;           float v0=dd[0]*d0*pj0, v1=dd[1]*d0*pj1, v2=dd[2]*d0*pj2, v3=dd[3]*d0*pj3;
;           if (!side1){ Zf[2*(lag0)+order]=v0; Zf[2*(lag0+1)+order]=v1; Zf[2*(lag0+2)+order]=v2; Zf[2*(lag0+3)+order]=v3; ssl+=v0*v0+v1*v1+v2*v2+v3*v3; }
;           else { if (lag0>=1){ Zf[2*(16384-lag0)+order]=v0; ssl+=v0*v0; }
;             Zf[2*(16384-lag0-1)+order]=v1; Zf[2*(16384-lag0-2)+order]=v2; Zf[2*(16384-lag0-3)+order]=v3; ssl+=v1*v1+v2*v2+v3*v3; } }
	v_mfma_f32_16x16x32_f16 v[8:11], v[236:239], v[0:3], 0
	v_mfma_f32_16x16x32_f16 v[8:11], v[240:243], v[4:7], v[8:11]
	global_load_dwordx4 v[236:239], v24, s[70:71]
	global_load_dwordx4 v[240:243], v24, s[70:71] offset:64
	v_add_u32_e32 v24, 0x4000, v24
	s_nop 4
	v_cndmask_b32_e64 v12, v8, v11, s[40:41]
	v_cndmask_b32_e64 v13, v9, v10, s[40:41]
	v_cndmask_b32_e64 v14, v10, v9, s[40:41]
	v_cndmask_b32_e64 v15, v11, v8, s[40:41]
	v_mul_f32_e32 v12, v12, v16
	v_mul_f32_e32 v13, v13, v16
	v_mul_f32_e32 v14, v14, v16
	v_mul_f32_e32 v15, v15, v16
	v_mul_f32_e32 v12, v20, v12
	v_mul_f32_e32 v13, v21, v13
	v_mul_f32_e32 v14, v22, v14
	v_mul_f32_e32 v15, v23, v15
	v_mul_f32_e32 v27, v12, v12
	v_fmac_f32_e32 v27, v13, v13
	v_fmac_f32_e32 v27, v14, v14
	v_fmac_f32_e32 v27, v15, v15
	v_add_f32_e32 v28, v28, v27
	s_mov_b64 exec, s[38:39]
	ds_write_b32 v18, v12
	ds_write_b32 v18, v13 offset:8
	ds_write_b32 v18, v14 offset:16
	ds_write_b32 v18, v15 offset:24
	s_mov_b64 exec, -1
	v_add_u32_e32 v18, v18, v19
	v_add_u32_e32 v17, 0x1600, v25
	v_cvt_f32_i32_e32 v17, v17
	v_mul_f32_e32 v17, v93, v17
	v_mul_f32_e32 v17, 0x3fb8aa3b, v17
	v_exp_f32_e32 v16, v17
	s_waitcnt vmcnt(4)
	v_mfma_f32_16x16x32_f16 v[8:11], v[244:247], v[0:3], 0
	v_mfma_f32_16x16x32_f16 v[8:11], v[248:251], v[4:7], v[8:11]
	global_load_dwordx4 v[244:247], v24, s[70:71]
	global_load_dwordx4 v[248:251], v24, s[70:71] offset:64
	v_add_u32_e32 v24, 0x4000, v24
	s_nop 4
	v_cndmask_b32_e64 v12, v8, v11, s[40:41]
	v_cndmask_b32_e64 v13, v9, v10, s[40:41]
	v_cndmask_b32_e64 v14, v10, v9, s[40:41]
	v_cndmask_b32_e64 v15, v11, v8, s[40:41]
	v_mul_f32_e32 v12, v12, v16
	v_mul_f32_e32 v13, v13, v16
	v_mul_f32_e32 v14, v14, v16
	v_mul_f32_e32 v15, v15, v16
	v_mul_f32_e32 v12, v20, v12
	v_mul_f32_e32 v13, v21, v13
	v_mul_f32_e32 v14, v22, v14
	v_mul_f32_e32 v15, v23, v15
	v_mul_f32_e32 v27, v12, v12
	v_fmac_f32_e32 v27, v13, v13
	v_fmac_f32_e32 v27, v14, v14
	v_fmac_f32_e32 v27, v15, v15
	v_add_f32_e32 v28, v28, v27
	s_mov_b64 exec, s[38:39]
	ds_write_b32 v18, v12
	ds_write_b32 v18, v13 offset:8
	ds_write_b32 v18, v14 offset:16
	ds_write_b32 v18, v15 offset:24
	s_mov_b64 exec, -1
	v_add_u32_e32 v18, v18, v19
	v_add_u32_e32 v17, 0x1680, v25
	v_cvt_f32_i32_e32 v17, v17
	v_mul_f32_e32 v17, v93, v17
	v_mul_f32_e32 v17, 0x3fb8aa3b, v17
	v_exp_f32_e32 v16, v17
	s_waitcnt vmcnt(4)
	v_mfma_f32_16x16x32_f16 v[8:11], v[228:231], v[0:3], 0
	v_mfma_f32_16x16x32_f16 v[8:11], v[232:235], v[4:7], v[8:11]
	global_load_dwordx4 v[228:231], v24, s[70:71]
	global_load_dwordx4 v[232:235], v24, s[70:71] offset:64
	v_add_u32_e32 v24, 0x4000, v24
	s_nop 4
	v_cndmask_b32_e64 v12, v8, v11, s[40:41]
	v_cndmask_b32_e64 v13, v9, v10, s[40:41]
	v_cndmask_b32_e64 v14, v10, v9, s[40:41]
	v_cndmask_b32_e64 v15, v11, v8, s[40:41]
	v_mul_f32_e32 v12, v12, v16
	v_mul_f32_e32 v13, v13, v16
	v_mul_f32_e32 v14, v14, v16
	v_mul_f32_e32 v15, v15, v16
	v_mul_f32_e32 v12, v20, v12
	v_mul_f32_e32 v13, v21, v13
	v_mul_f32_e32 v14, v22, v14
	v_mul_f32_e32 v15, v23, v15
	v_mul_f32_e32 v27, v12, v12
	v_fmac_f32_e32 v27, v13, v13
	v_fmac_f32_e32 v27, v14, v14
	v_fmac_f32_e32 v27, v15, v15
	v_add_f32_e32 v28, v28, v27
	s_mov_b64 exec, s[38:39]
	ds_write_b32 v18, v12
	ds_write_b32 v18, v13 offset:8
	ds_write_b32 v18, v14 offset:16
	ds_write_b32 v18, v15 offset:24
	s_mov_b64 exec, -1
	v_add_u32_e32 v18, v18, v19
	v_add_u32_e32 v17, 0x1700, v25
	v_cvt_f32_i32_e32 v17, v17
	v_mul_f32_e32 v17, v93, v17
	v_mul_f32_e32 v17, 0x3fb8aa3b, v17
	v_exp_f32_e32 v16, v17
	s_waitcnt vmcnt(4)
	v_mfma_f32_16x16x32_f16 v[8:11], v[236:239], v[0:3], 0
	v_mfma_f32_16x16x32_f16 v[8:11], v[240:243], v[4:7], v[8:11]
	global_load_dwordx4 v[236:239], v24, s[70:71]
	global_load_dwordx4 v[240:243], v24, s[70:71] offset:64
	v_add_u32_e32 v24, 0x4000, v24
	s_nop 4
	v_cndmask_b32_e64 v12, v8, v11, s[40:41]
	v_cndmask_b32_e64 v13, v9, v10, s[40:41]
	v_cndmask_b32_e64 v14, v10, v9, s[40:41]
	v_cndmask_b32_e64 v15, v11, v8, s[40:41]
	v_mul_f32_e32 v12, v12, v16
	v_mul_f32_e32 v13, v13, v16
	v_mul_f32_e32 v14, v14, v16
	v_mul_f32_e32 v15, v15, v16
	v_mul_f32_e32 v12, v20, v12
	v_mul_f32_e32 v13, v21, v13
	v_mul_f32_e32 v14, v22, v14
	v_mul_f32_e32 v15, v23, v15
	v_mul_f32_e32 v27, v12, v12
	v_fmac_f32_e32 v27, v13, v13
	v_fmac_f32_e32 v27, v14, v14
	v_fmac_f32_e32 v27, v15, v15
	v_add_f32_e32 v28, v28, v27
	s_mov_b64 exec, s[38:39]
	ds_write_b32 v18, v12
	ds_write_b32 v18, v13 offset:8
	ds_write_b32 v18, v14 offset:16
	ds_write_b32 v18, v15 offset:24
	s_mov_b64 exec, -1
	v_add_u32_e32 v18, v18, v19
	v_add_u32_e32 v17, 0x1780, v25
	v_cvt_f32_i32_e32 v17, v17
	v_mul_f32_e32 v17, v93, v17
	v_mul_f32_e32 v17, 0x3fb8aa3b, v17
	v_exp_f32_e32 v16, v17
	s_waitcnt vmcnt(4)
	v_mfma_f32_16x16x32_f16 v[8:11], v[244:247], v[0:3], 0
	v_mfma_f32_16x16x32_f16 v[8:11], v[248:251], v[4:7], v[8:11]
	global_load_dwordx4 v[244:247], v24, s[70:71]
	global_load_dwordx4 v[248:251], v24, s[70:71] offset:64
	v_add_u32_e32 v24, 0x4000, v24
	s_nop 4
	v_cndmask_b32_e64 v12, v8, v11, s[40:41]
	v_cndmask_b32_e64 v13, v9, v10, s[40:41]
	v_cndmask_b32_e64 v14, v10, v9, s[40:41]
	v_cndmask_b32_e64 v15, v11, v8, s[40:41]
	v_mul_f32_e32 v12, v12, v16
	v_mul_f32_e32 v13, v13, v16
	v_mul_f32_e32 v14, v14, v16
	v_mul_f32_e32 v15, v15, v16
	v_mul_f32_e32 v12, v20, v12
	v_mul_f32_e32 v13, v21, v13
	v_mul_f32_e32 v14, v22, v14
	v_mul_f32_e32 v15, v23, v15
	v_mul_f32_e32 v27, v12, v12
	v_fmac_f32_e32 v27, v13, v13
	v_fmac_f32_e32 v27, v14, v14
	v_fmac_f32_e32 v27, v15, v15
	v_add_f32_e32 v28, v28, v27
	s_mov_b64 exec, s[38:39]
	ds_write_b32 v18, v12
	ds_write_b32 v18, v13 offset:8
	ds_write_b32 v18, v14 offset:16
	ds_write_b32 v18, v15 offset:24
	s_mov_b64 exec, -1
	v_add_u32_e32 v18, v18, v19
	v_add_u32_e32 v17, 0x1800, v25
	v_cvt_f32_i32_e32 v17, v17
	v_mul_f32_e32 v17, v93, v17
	v_mul_f32_e32 v17, 0x3fb8aa3b, v17
	v_exp_f32_e32 v16, v17
	s_waitcnt vmcnt(4)
; __device__ __forceinline__ void phase_hyena(KP kp_, int hf){ asm volatile("" : "+s"(kp_)); const Params p=load_params(kp_);
;     ...
;       _Pragma("unroll 8") for (int i=0;i<64;++i){ int tl=wid+8*i;
;         const _Float16* ap=a3+(size_t)(tl*16+n)*64+kg*8;
;         f16x8 a0=*(const f16x8*)ap, a1=*(const f16x8*)(ap+32);
;         f32x4 dd={0.f,0.f,0.f,0.f};
;         dd=__builtin_amdgcn_mfma_f32_16x16x32_f16(a0,bw0,dd,0,0,0);
;         dd=__builtin_amdgcn_mfma_f32_16x16x32_f16(a1,bw1,dd,0,0,0);
;         if (n<4){ float d0=__expf(dsc*(float)(tl*16)); int lag0=tl*16+kg*4;
;           float v0=dd[0]*d0*pj0, v1=dd[1]*d0*pj1, v2=dd[2]*d0*pj2, v3=dd[3]*d0*pj3;
;           if (!side1){ Zf[2*(lag0)+order]=v0; Zf[2*(lag0+1)+order]=v1; Zf[2*(lag0+2)+order]=v2; Zf[2*(lag0+3)+order]=v3; ssl+=v0*v0+v1*v1+v2*v2+v3*v3; }
;           else { if (lag0>=1){ Zf[2*(16384-lag0)+order]=v0; ssl+=v0*v0; }
;             Zf[2*(16384-lag0-1)+order]=v1; Zf[2*(16384-lag0-2)+order]=v2; Zf[2*(16384-lag0-3)+order]=v3; ssl+=v1*v1+v2*v2+v3*v3; } }
	v_mfma_f32_16x16x32_f16 v[8:11], v[228:231], v[0:3], 0
	v_mfma_f32_16x16x32_f16 v[8:11], v[232:235], v[4:7], v[8:11]
	global_load_dwordx4 v[228:231], v24, s[70:71]
	global_load_dwordx4 v[232:235], v24, s[70:71] offset:64
	v_add_u32_e32 v24, 0x4000, v24
	s_nop 4
	v_cndmask_b32_e64 v12, v8, v11, s[40:41]
	v_cndmask_b32_e64 v13, v9, v10, s[40:41]
	v_cndmask_b32_e64 v14, v10, v9, s[40:41]
	v_cndmask_b32_e64 v15, v11, v8, s[40:41]
	v_mul_f32_e32 v12, v12, v16
	v_mul_f32_e32 v13, v13, v16
	v_mul_f32_e32 v14, v14, v16
	v_mul_f32_e32 v15, v15, v16
	v_mul_f32_e32 v12, v20, v12
	v_mul_f32_e32 v13, v21, v13
	v_mul_f32_e32 v14, v22, v14
	v_mul_f32_e32 v15, v23, v15
	v_mul_f32_e32 v27, v12, v12
	v_fmac_f32_e32 v27, v13, v13
	v_fmac_f32_e32 v27, v14, v14
	v_fmac_f32_e32 v27, v15, v15
	v_add_f32_e32 v28, v28, v27
	s_mov_b64 exec, s[38:39]
	ds_write_b32 v18, v12
	ds_write_b32 v18, v13 offset:8
	ds_write_b32 v18, v14 offset:16
	ds_write_b32 v18, v15 offset:24
	s_mov_b64 exec, -1
	v_add_u32_e32 v18, v18, v19
	v_add_u32_e32 v17, 0x1880, v25
	v_cvt_f32_i32_e32 v17, v17
	v_mul_f32_e32 v17, v93, v17
	v_mul_f32_e32 v17, 0x3fb8aa3b, v17
	v_exp_f32_e32 v16, v17
	s_waitcnt vmcnt(4)
	v_mfma_f32_16x16x32_f16 v[8:11], v[236:239], v[0:3], 0
	v_mfma_f32_16x16x32_f16 v[8:11], v[240:243], v[4:7], v[8:11]
	global_load_dwordx4 v[236:239], v24, s[70:71]
	global_load_dwordx4 v[240:243], v24, s[70:71] offset:64
	v_add_u32_e32 v24, 0x4000, v24
	s_nop 4
	v_cndmask_b32_e64 v12, v8, v11, s[40:41]
	v_cndmask_b32_e64 v13, v9, v10, s[40:41]
	v_cndmask_b32_e64 v14, v10, v9, s[40:41]
	v_cndmask_b32_e64 v15, v11, v8, s[40:41]
	v_mul_f32_e32 v12, v12, v16
	v_mul_f32_e32 v13, v13, v16
	v_mul_f32_e32 v14, v14, v16
	v_mul_f32_e32 v15, v15, v16
	v_mul_f32_e32 v12, v20, v12
	v_mul_f32_e32 v13, v21, v13
	v_mul_f32_e32 v14, v22, v14
	v_mul_f32_e32 v15, v23, v15
	v_mul_f32_e32 v27, v12, v12
	v_fmac_f32_e32 v27, v13, v13
	v_fmac_f32_e32 v27, v14, v14
	v_fmac_f32_e32 v27, v15, v15
	v_add_f32_e32 v28, v28, v27
	s_mov_b64 exec, s[38:39]
	ds_write_b32 v18, v12
	ds_write_b32 v18, v13 offset:8
	ds_write_b32 v18, v14 offset:16
	ds_write_b32 v18, v15 offset:24
	s_mov_b64 exec, -1
	v_add_u32_e32 v18, v18, v19
	v_add_u32_e32 v17, 0x1900, v25
	v_cvt_f32_i32_e32 v17, v17
	v_mul_f32_e32 v17, v93, v17
	v_mul_f32_e32 v17, 0x3fb8aa3b, v17
	v_exp_f32_e32 v16, v17
	s_waitcnt vmcnt(4)
	v_mfma_f32_16x16x32_f16 v[8:11], v[244:247], v[0:3], 0
	v_mfma_f32_16x16x32_f16 v[8:11], v[248:251], v[4:7], v[8:11]
	global_load_dwordx4 v[244:247], v24, s[70:71]
	global_load_dwordx4 v[248:251], v24, s[70:71] offset:64
	v_add_u32_e32 v24, 0x4000, v24
	s_nop 4
	v_cndmask_b32_e64 v12, v8, v11, s[40:41]
	v_cndmask_b32_e64 v13, v9, v10, s[40:41]
	v_cndmask_b32_e64 v14, v10, v9, s[40:41]
	v_cndmask_b32_e64 v15, v11, v8, s[40:41]
	v_mul_f32_e32 v12, v12, v16
	v_mul_f32_e32 v13, v13, v16
	v_mul_f32_e32 v14, v14, v16
	v_mul_f32_e32 v15, v15, v16
	v_mul_f32_e32 v12, v20, v12
	v_mul_f32_e32 v13, v21, v13
	v_mul_f32_e32 v14, v22, v14
	v_mul_f32_e32 v15, v23, v15
	v_mul_f32_e32 v27, v12, v12
	v_fmac_f32_e32 v27, v13, v13
	v_fmac_f32_e32 v27, v14, v14
	v_fmac_f32_e32 v27, v15, v15
	v_add_f32_e32 v28, v28, v27
	s_mov_b64 exec, s[38:39]
	ds_write_b32 v18, v12
	ds_write_b32 v18, v13 offset:8
	ds_write_b32 v18, v14 offset:16
	ds_write_b32 v18, v15 offset:24
	s_mov_b64 exec, -1
	v_add_u32_e32 v18, v18, v19
	v_add_u32_e32 v17, 0x1980, v25
	v_cvt_f32_i32_e32 v17, v17
	v_mul_f32_e32 v17, v93, v17
	v_mul_f32_e32 v17, 0x3fb8aa3b, v17
	v_exp_f32_e32 v16, v17
	s_waitcnt vmcnt(4)
	v_mfma_f32_16x16x32_f16 v[8:11], v[228:231], v[0:3], 0
	v_mfma_f32_16x16x32_f16 v[8:11], v[232:235], v[4:7], v[8:11]
	global_load_dwordx4 v[228:231], v24, s[70:71]
	global_load_dwordx4 v[232:235], v24, s[70:71] offset:64
	v_add_u32_e32 v24, 0x4000, v24
	s_nop 4
	v_cndmask_b32_e64 v12, v8, v11, s[40:41]
	v_cndmask_b32_e64 v13, v9, v10, s[40:41]
	v_cndmask_b32_e64 v14, v10, v9, s[40:41]
	v_cndmask_b32_e64 v15, v11, v8, s[40:41]
	v_mul_f32_e32 v12, v12, v16
	v_mul_f32_e32 v13, v13, v16
	v_mul_f32_e32 v14, v14, v16
	v_mul_f32_e32 v15, v15, v16
	v_mul_f32_e32 v12, v20, v12
	v_mul_f32_e32 v13, v21, v13
	v_mul_f32_e32 v14, v22, v14
	v_mul_f32_e32 v15, v23, v15
	v_mul_f32_e32 v27, v12, v12
	v_fmac_f32_e32 v27, v13, v13
	v_fmac_f32_e32 v27, v14, v14
	v_fmac_f32_e32 v27, v15, v15
	v_add_f32_e32 v28, v28, v27
	s_mov_b64 exec, s[38:39]
	ds_write_b32 v18, v12
	ds_write_b32 v18, v13 offset:8
	ds_write_b32 v18, v14 offset:16
	ds_write_b32 v18, v15 offset:24
	s_mov_b64 exec, -1
	v_add_u32_e32 v18, v18, v19
	v_add_u32_e32 v17, 0x1a00, v25
	v_cvt_f32_i32_e32 v17, v17
	v_mul_f32_e32 v17, v93, v17
	v_mul_f32_e32 v17, 0x3fb8aa3b, v17
	v_exp_f32_e32 v16, v17
	s_waitcnt vmcnt(4)
	v_mfma_f32_16x16x32_f16 v[8:11], v[236:239], v[0:3], 0
	v_mfma_f32_16x16x32_f16 v[8:11], v[240:243], v[4:7], v[8:11]
	global_load_dwordx4 v[236:239], v24, s[70:71]
	global_load_dwordx4 v[240:243], v24, s[70:71] offset:64
	v_add_u32_e32 v24, 0x4000, v24
	s_nop 4
	v_cndmask_b32_e64 v12, v8, v11, s[40:41]
	v_cndmask_b32_e64 v13, v9, v10, s[40:41]
	v_cndmask_b32_e64 v14, v10, v9, s[40:41]
	v_cndmask_b32_e64 v15, v11, v8, s[40:41]
	v_mul_f32_e32 v12, v12, v16
	v_mul_f32_e32 v13, v13, v16
	v_mul_f32_e32 v14, v14, v16
	v_mul_f32_e32 v15, v15, v16
	v_mul_f32_e32 v12, v20, v12
	v_mul_f32_e32 v13, v21, v13
	v_mul_f32_e32 v14, v22, v14
	v_mul_f32_e32 v15, v23, v15
	v_mul_f32_e32 v27, v12, v12
	v_fmac_f32_e32 v27, v13, v13
	v_fmac_f32_e32 v27, v14, v14
	v_fmac_f32_e32 v27, v15, v15
	v_add_f32_e32 v28, v28, v27
	s_mov_b64 exec, s[38:39]
	ds_write_b32 v18, v12
	ds_write_b32 v18, v13 offset:8
	ds_write_b32 v18, v14 offset:16
	ds_write_b32 v18, v15 offset:24
	s_mov_b64 exec, -1
	v_add_u32_e32 v18, v18, v19
	v_add_u32_e32 v17, 0x1a80, v25
	v_cvt_f32_i32_e32 v17, v17
	v_mul_f32_e32 v17, v93, v17
	v_mul_f32_e32 v17, 0x3fb8aa3b, v17
	v_exp_f32_e32 v16, v17
	s_waitcnt vmcnt(4)
; __device__ __forceinline__ void phase_hyena(KP kp_, int hf){ asm volatile("" : "+s"(kp_)); const Params p=load_params(kp_);
;     ...
;       _Pragma("unroll 8") for (int i=0;i<64;++i){ int tl=wid+8*i;
;         const _Float16* ap=a3+(size_t)(tl*16+n)*64+kg*8;
;         f16x8 a0=*(const f16x8*)ap, a1=*(const f16x8*)(ap+32);
;         f32x4 dd={0.f,0.f,0.f,0.f};
;         dd=__builtin_amdgcn_mfma_f32_16x16x32_f16(a0,bw0,dd,0,0,0);
;         dd=__builtin_amdgcn_mfma_f32_16x16x32_f16(a1,bw1,dd,0,0,0);
;         if (n<4){ float d0=__expf(dsc*(float)(tl*16)); int lag0=tl*16+kg*4;
;           float v0=dd[0]*d0*pj0, v1=dd[1]*d0*pj1, v2=dd[2]*d0*pj2, v3=dd[3]*d0*pj3;
;           if (!side1){ Zf[2*(lag0)+order]=v0; Zf[2*(lag0+1)+order]=v1; Zf[2*(lag0+2)+order]=v2; Zf[2*(lag0+3)+order]=v3; ssl+=v0*v0+v1*v1+v2*v2+v3*v3; }
;           else { if (lag0>=1){ Zf[2*(16384-lag0)+order]=v0; ssl+=v0*v0; }
;             Zf[2*(16384-lag0-1)+order]=v1; Zf[2*(16384-lag0-2)+order]=v2; Zf[2*(16384-lag0-3)+order]=v3; ssl+=v1*v1+v2*v2+v3*v3; } }
	v_mfma_f32_16x16x32_f16 v[8:11], v[244:247], v[0:3], 0
	v_mfma_f32_16x16x32_f16 v[8:11], v[248:251], v[4:7], v[8:11]
	global_load_dwordx4 v[244:247], v24, s[70:71]
	global_load_dwordx4 v[248:251], v24, s[70:71] offset:64
	v_add_u32_e32 v24, 0x4000, v24
	s_nop 4
	v_cndmask_b32_e64 v12, v8, v11, s[40:41]
	v_cndmask_b32_e64 v13, v9, v10, s[40:41]
	v_cndmask_b32_e64 v14, v10, v9, s[40:41]
	v_cndmask_b32_e64 v15, v11, v8, s[40:41]
	v_mul_f32_e32 v12, v12, v16
	v_mul_f32_e32 v13, v13, v16
	v_mul_f32_e32 v14, v14, v16
	v_mul_f32_e32 v15, v15, v16
	v_mul_f32_e32 v12, v20, v12
	v_mul_f32_e32 v13, v21, v13
	v_mul_f32_e32 v14, v22, v14
	v_mul_f32_e32 v15, v23, v15
	v_mul_f32_e32 v27, v12, v12
	v_fmac_f32_e32 v27, v13, v13
	v_fmac_f32_e32 v27, v14, v14
	v_fmac_f32_e32 v27, v15, v15
	v_add_f32_e32 v28, v28, v27
	s_mov_b64 exec, s[38:39]
	ds_write_b32 v18, v12
	ds_write_b32 v18, v13 offset:8
	ds_write_b32 v18, v14 offset:16
	ds_write_b32 v18, v15 offset:24
	s_mov_b64 exec, -1
	v_add_u32_e32 v18, v18, v19
	v_add_u32_e32 v17, 0x1b00, v25
	v_cvt_f32_i32_e32 v17, v17
	v_mul_f32_e32 v17, v93, v17
	v_mul_f32_e32 v17, 0x3fb8aa3b, v17
	v_exp_f32_e32 v16, v17
	s_waitcnt vmcnt(4)
	v_mfma_f32_16x16x32_f16 v[8:11], v[228:231], v[0:3], 0
	v_mfma_f32_16x16x32_f16 v[8:11], v[232:235], v[4:7], v[8:11]
	global_load_dwordx4 v[228:231], v24, s[70:71]
	global_load_dwordx4 v[232:235], v24, s[70:71] offset:64
	v_add_u32_e32 v24, 0x4000, v24
	s_nop 4
	v_cndmask_b32_e64 v12, v8, v11, s[40:41]
	v_cndmask_b32_e64 v13, v9, v10, s[40:41]
	v_cndmask_b32_e64 v14, v10, v9, s[40:41]
	v_cndmask_b32_e64 v15, v11, v8, s[40:41]
	v_mul_f32_e32 v12, v12, v16
	v_mul_f32_e32 v13, v13, v16
	v_mul_f32_e32 v14, v14, v16
	v_mul_f32_e32 v15, v15, v16
	v_mul_f32_e32 v12, v20, v12
	v_mul_f32_e32 v13, v21, v13
	v_mul_f32_e32 v14, v22, v14
	v_mul_f32_e32 v15, v23, v15
	v_mul_f32_e32 v27, v12, v12
	v_fmac_f32_e32 v27, v13, v13
	v_fmac_f32_e32 v27, v14, v14
	v_fmac_f32_e32 v27, v15, v15
	v_add_f32_e32 v28, v28, v27
	s_mov_b64 exec, s[38:39]
	ds_write_b32 v18, v12
	ds_write_b32 v18, v13 offset:8
	ds_write_b32 v18, v14 offset:16
	ds_write_b32 v18, v15 offset:24
	s_mov_b64 exec, -1
	v_add_u32_e32 v18, v18, v19
	v_add_u32_e32 v17, 0x1b80, v25
	v_cvt_f32_i32_e32 v17, v17
	v_mul_f32_e32 v17, v93, v17
	v_mul_f32_e32 v17, 0x3fb8aa3b, v17
	v_exp_f32_e32 v16, v17
	s_waitcnt vmcnt(4)
	v_mfma_f32_16x16x32_f16 v[8:11], v[236:239], v[0:3], 0
	v_mfma_f32_16x16x32_f16 v[8:11], v[240:243], v[4:7], v[8:11]
	global_load_dwordx4 v[236:239], v24, s[70:71]
	global_load_dwordx4 v[240:243], v24, s[70:71] offset:64
	v_add_u32_e32 v24, 0x4000, v24
	s_nop 4
	v_cndmask_b32_e64 v12, v8, v11, s[40:41]
	v_cndmask_b32_e64 v13, v9, v10, s[40:41]
	v_cndmask_b32_e64 v14, v10, v9, s[40:41]
	v_cndmask_b32_e64 v15, v11, v8, s[40:41]
	v_mul_f32_e32 v12, v12, v16
	v_mul_f32_e32 v13, v13, v16
	v_mul_f32_e32 v14, v14, v16
	v_mul_f32_e32 v15, v15, v16
	v_mul_f32_e32 v12, v20, v12
	v_mul_f32_e32 v13, v21, v13
	v_mul_f32_e32 v14, v22, v14
	v_mul_f32_e32 v15, v23, v15
	v_mul_f32_e32 v27, v12, v12
	v_fmac_f32_e32 v27, v13, v13
	v_fmac_f32_e32 v27, v14, v14
	v_fmac_f32_e32 v27, v15, v15
	v_add_f32_e32 v28, v28, v27
	s_mov_b64 exec, s[38:39]
	ds_write_b32 v18, v12
	ds_write_b32 v18, v13 offset:8
	ds_write_b32 v18, v14 offset:16
	ds_write_b32 v18, v15 offset:24
	s_mov_b64 exec, -1
	v_add_u32_e32 v18, v18, v19
	v_add_u32_e32 v17, 0x1c00, v25
	v_cvt_f32_i32_e32 v17, v17
	v_mul_f32_e32 v17, v93, v17
	v_mul_f32_e32 v17, 0x3fb8aa3b, v17
	v_exp_f32_e32 v16, v17
	s_waitcnt vmcnt(4)
	v_mfma_f32_16x16x32_f16 v[8:11], v[244:247], v[0:3], 0
	v_mfma_f32_16x16x32_f16 v[8:11], v[248:251], v[4:7], v[8:11]
	global_load_dwordx4 v[244:247], v24, s[70:71]
	global_load_dwordx4 v[248:251], v24, s[70:71] offset:64
	v_add_u32_e32 v24, 0x4000, v24
	s_nop 4
	v_cndmask_b32_e64 v12, v8, v11, s[40:41]
	v_cndmask_b32_e64 v13, v9, v10, s[40:41]
	v_cndmask_b32_e64 v14, v10, v9, s[40:41]
	v_cndmask_b32_e64 v15, v11, v8, s[40:41]
	v_mul_f32_e32 v12, v12, v16
	v_mul_f32_e32 v13, v13, v16
	v_mul_f32_e32 v14, v14, v16
	v_mul_f32_e32 v15, v15, v16
	v_mul_f32_e32 v12, v20, v12
	v_mul_f32_e32 v13, v21, v13
	v_mul_f32_e32 v14, v22, v14
	v_mul_f32_e32 v15, v23, v15
	v_mul_f32_e32 v27, v12, v12
	v_fmac_f32_e32 v27, v13, v13
	v_fmac_f32_e32 v27, v14, v14
	v_fmac_f32_e32 v27, v15, v15
	v_add_f32_e32 v28, v28, v27
	s_mov_b64 exec, s[38:39]
	ds_write_b32 v18, v12
	ds_write_b32 v18, v13 offset:8
	ds_write_b32 v18, v14 offset:16
	ds_write_b32 v18, v15 offset:24
	s_mov_b64 exec, -1
	v_add_u32_e32 v18, v18, v19
	v_add_u32_e32 v17, 0x1c80, v25
	v_cvt_f32_i32_e32 v17, v17
	v_mul_f32_e32 v17, v93, v17
	v_mul_f32_e32 v17, 0x3fb8aa3b, v17
	v_exp_f32_e32 v16, v17
	s_waitcnt vmcnt(4)
	v_mfma_f32_16x16x32_f16 v[8:11], v[228:231], v[0:3], 0
	v_mfma_f32_16x16x32_f16 v[8:11], v[232:235], v[4:7], v[8:11]
	global_load_dwordx4 v[228:231], v24, s[70:71]
	global_load_dwordx4 v[232:235], v24, s[70:71] offset:64
	v_add_u32_e32 v24, 0x4000, v24
	s_nop 4
	v_cndmask_b32_e64 v12, v8, v11, s[40:41]
	v_cndmask_b32_e64 v13, v9, v10, s[40:41]
	v_cndmask_b32_e64 v14, v10, v9, s[40:41]
	v_cndmask_b32_e64 v15, v11, v8, s[40:41]
	v_mul_f32_e32 v12, v12, v16
	v_mul_f32_e32 v13, v13, v16
	v_mul_f32_e32 v14, v14, v16
	v_mul_f32_e32 v15, v15, v16
	v_mul_f32_e32 v12, v20, v12
	v_mul_f32_e32 v13, v21, v13
	v_mul_f32_e32 v14, v22, v14
	v_mul_f32_e32 v15, v23, v15
	v_mul_f32_e32 v27, v12, v12
	v_fmac_f32_e32 v27, v13, v13
	v_fmac_f32_e32 v27, v14, v14
	v_fmac_f32_e32 v27, v15, v15
	v_add_f32_e32 v28, v28, v27
	s_mov_b64 exec, s[38:39]
	ds_write_b32 v18, v12
	ds_write_b32 v18, v13 offset:8
	ds_write_b32 v18, v14 offset:16
	ds_write_b32 v18, v15 offset:24
	s_mov_b64 exec, -1
	v_add_u32_e32 v18, v18, v19
	v_add_u32_e32 v17, 0x1d00, v25
	v_cvt_f32_i32_e32 v17, v17
	v_mul_f32_e32 v17, v93, v17
	v_mul_f32_e32 v17, 0x3fb8aa3b, v17
	v_exp_f32_e32 v16, v17
	s_waitcnt vmcnt(4)
; __device__ __forceinline__ void phase_hyena(KP kp_, int hf){ asm volatile("" : "+s"(kp_)); const Params p=load_params(kp_);
;     ...
;       _Pragma("unroll 8") for (int i=0;i<64;++i){ int tl=wid+8*i;
;         const _Float16* ap=a3+(size_t)(tl*16+n)*64+kg*8;
;         f16x8 a0=*(const f16x8*)ap, a1=*(const f16x8*)(ap+32);
;         f32x4 dd={0.f,0.f,0.f,0.f};
;         dd=__builtin_amdgcn_mfma_f32_16x16x32_f16(a0,bw0,dd,0,0,0);
;         dd=__builtin_amdgcn_mfma_f32_16x16x32_f16(a1,bw1,dd,0,0,0);
;         if (n<4){ float d0=__expf(dsc*(float)(tl*16)); int lag0=tl*16+kg*4;
;           float v0=dd[0]*d0*pj0, v1=dd[1]*d0*pj1, v2=dd[2]*d0*pj2, v3=dd[3]*d0*pj3;
;           if (!side1){ Zf[2*(lag0)+order]=v0; Zf[2*(lag0+1)+order]=v1; Zf[2*(lag0+2)+order]=v2; Zf[2*(lag0+3)+order]=v3; ssl+=v0*v0+v1*v1+v2*v2+v3*v3; }
;           else { if (lag0>=1){ Zf[2*(16384-lag0)+order]=v0; ssl+=v0*v0; }
;             Zf[2*(16384-lag0-1)+order]=v1; Zf[2*(16384-lag0-2)+order]=v2; Zf[2*(16384-lag0-3)+order]=v3; ssl+=v1*v1+v2*v2+v3*v3; } }
;       }
;       ss0=(n<4 && order==0)?ssl:0.f; ss1=(n<4 && order==1)?ssl:0.f;
;     }
;     if (tid==0) Z[8192]=make_float2(0.f,0.f);
	v_mfma_f32_16x16x32_f16 v[8:11], v[236:239], v[0:3], 0
	v_mfma_f32_16x16x32_f16 v[8:11], v[240:243], v[4:7], v[8:11]
	global_load_dwordx4 v[236:239], v24, s[70:71]
	global_load_dwordx4 v[240:243], v24, s[70:71] offset:64
	v_add_u32_e32 v24, 0x4000, v24
	s_nop 4
	v_cndmask_b32_e64 v12, v8, v11, s[40:41]
	v_cndmask_b32_e64 v13, v9, v10, s[40:41]
	v_cndmask_b32_e64 v14, v10, v9, s[40:41]
	v_cndmask_b32_e64 v15, v11, v8, s[40:41]
	v_mul_f32_e32 v12, v12, v16
	v_mul_f32_e32 v13, v13, v16
	v_mul_f32_e32 v14, v14, v16
	v_mul_f32_e32 v15, v15, v16
	v_mul_f32_e32 v12, v20, v12
	v_mul_f32_e32 v13, v21, v13
	v_mul_f32_e32 v14, v22, v14
	v_mul_f32_e32 v15, v23, v15
	v_mul_f32_e32 v27, v12, v12
	v_fmac_f32_e32 v27, v13, v13
	v_fmac_f32_e32 v27, v14, v14
	v_fmac_f32_e32 v27, v15, v15
	v_add_f32_e32 v28, v28, v27
	s_mov_b64 exec, s[38:39]
	ds_write_b32 v18, v12
	ds_write_b32 v18, v13 offset:8
	ds_write_b32 v18, v14 offset:16
	ds_write_b32 v18, v15 offset:24
	s_mov_b64 exec, -1
	v_add_u32_e32 v18, v18, v19
	v_add_u32_e32 v17, 0x1d80, v25
	v_cvt_f32_i32_e32 v17, v17
	v_mul_f32_e32 v17, v93, v17
	v_mul_f32_e32 v17, 0x3fb8aa3b, v17
	v_exp_f32_e32 v16, v17
	s_waitcnt vmcnt(4)
	v_mfma_f32_16x16x32_f16 v[8:11], v[244:247], v[0:3], 0
	v_mfma_f32_16x16x32_f16 v[8:11], v[248:251], v[4:7], v[8:11]
	global_load_dwordx4 v[244:247], v24, s[70:71]
	global_load_dwordx4 v[248:251], v24, s[70:71] offset:64
	v_add_u32_e32 v24, 0x4000, v24
	s_nop 4
	v_cndmask_b32_e64 v12, v8, v11, s[40:41]
	v_cndmask_b32_e64 v13, v9, v10, s[40:41]
	v_cndmask_b32_e64 v14, v10, v9, s[40:41]
	v_cndmask_b32_e64 v15, v11, v8, s[40:41]
	v_mul_f32_e32 v12, v12, v16
	v_mul_f32_e32 v13, v13, v16
	v_mul_f32_e32 v14, v14, v16
	v_mul_f32_e32 v15, v15, v16
	v_mul_f32_e32 v12, v20, v12
	v_mul_f32_e32 v13, v21, v13
	v_mul_f32_e32 v14, v22, v14
	v_mul_f32_e32 v15, v23, v15
	v_mul_f32_e32 v27, v12, v12
	v_fmac_f32_e32 v27, v13, v13
	v_fmac_f32_e32 v27, v14, v14
	v_fmac_f32_e32 v27, v15, v15
	v_add_f32_e32 v28, v28, v27
	s_mov_b64 exec, s[38:39]
	ds_write_b32 v18, v12
	ds_write_b32 v18, v13 offset:8
	ds_write_b32 v18, v14 offset:16
	ds_write_b32 v18, v15 offset:24
	s_mov_b64 exec, -1
	v_add_u32_e32 v18, v18, v19
	v_add_u32_e32 v17, 0x1e00, v25
	v_cvt_f32_i32_e32 v17, v17
	v_mul_f32_e32 v17, v93, v17
	v_mul_f32_e32 v17, 0x3fb8aa3b, v17
	v_exp_f32_e32 v16, v17
	s_waitcnt vmcnt(4)
	v_mfma_f32_16x16x32_f16 v[8:11], v[228:231], v[0:3], 0
	v_mfma_f32_16x16x32_f16 v[8:11], v[232:235], v[4:7], v[8:11]
	global_load_dwordx4 v[228:231], v24, s[70:71]
	global_load_dwordx4 v[232:235], v24, s[70:71] offset:64
	v_add_u32_e32 v24, 0x4000, v24
	s_nop 4
	v_cndmask_b32_e64 v12, v8, v11, s[40:41]
	v_cndmask_b32_e64 v13, v9, v10, s[40:41]
	v_cndmask_b32_e64 v14, v10, v9, s[40:41]
	v_cndmask_b32_e64 v15, v11, v8, s[40:41]
	v_mul_f32_e32 v12, v12, v16
	v_mul_f32_e32 v13, v13, v16
	v_mul_f32_e32 v14, v14, v16
	v_mul_f32_e32 v15, v15, v16
	v_mul_f32_e32 v12, v20, v12
	v_mul_f32_e32 v13, v21, v13
	v_mul_f32_e32 v14, v22, v14
	v_mul_f32_e32 v15, v23, v15
	v_mul_f32_e32 v27, v12, v12
	v_fmac_f32_e32 v27, v13, v13
	v_fmac_f32_e32 v27, v14, v14
	v_fmac_f32_e32 v27, v15, v15
	v_add_f32_e32 v28, v28, v27
	s_mov_b64 exec, s[38:39]
	ds_write_b32 v18, v12
	ds_write_b32 v18, v13 offset:8
	ds_write_b32 v18, v14 offset:16
	ds_write_b32 v18, v15 offset:24
	s_mov_b64 exec, -1
	v_add_u32_e32 v18, v18, v19
	v_add_u32_e32 v17, 0x1e80, v25
	v_cvt_f32_i32_e32 v17, v17
	v_mul_f32_e32 v17, v93, v17
	v_mul_f32_e32 v17, 0x3fb8aa3b, v17
	v_exp_f32_e32 v16, v17
	s_waitcnt vmcnt(4)
	v_mfma_f32_16x16x32_f16 v[8:11], v[236:239], v[0:3], 0
	v_mfma_f32_16x16x32_f16 v[8:11], v[240:243], v[4:7], v[8:11]
	s_nop 2
	s_nop 4
	v_cndmask_b32_e64 v12, v8, v11, s[40:41]
	v_cndmask_b32_e64 v13, v9, v10, s[40:41]
	v_cndmask_b32_e64 v14, v10, v9, s[40:41]
	v_cndmask_b32_e64 v15, v11, v8, s[40:41]
	v_mul_f32_e32 v12, v12, v16
	v_mul_f32_e32 v13, v13, v16
	v_mul_f32_e32 v14, v14, v16
	v_mul_f32_e32 v15, v15, v16
	v_mul_f32_e32 v12, v20, v12
	v_mul_f32_e32 v13, v21, v13
	v_mul_f32_e32 v14, v22, v14
	v_mul_f32_e32 v15, v23, v15
	v_mul_f32_e32 v27, v12, v12
	v_fmac_f32_e32 v27, v13, v13
	v_fmac_f32_e32 v27, v14, v14
	v_fmac_f32_e32 v27, v15, v15
	v_add_f32_e32 v28, v28, v27
	s_mov_b64 exec, s[38:39]
	ds_write_b32 v18, v12
	ds_write_b32 v18, v13 offset:8
	ds_write_b32 v18, v14 offset:16
	ds_write_b32 v18, v15 offset:24
	s_mov_b64 exec, -1
	v_add_u32_e32 v18, v18, v19
	v_add_u32_e32 v17, 0x1f00, v25
	v_cvt_f32_i32_e32 v17, v17
	v_mul_f32_e32 v17, v93, v17
	v_mul_f32_e32 v17, 0x3fb8aa3b, v17
	v_exp_f32_e32 v16, v17
	s_waitcnt vmcnt(2)
	v_mfma_f32_16x16x32_f16 v[8:11], v[244:247], v[0:3], 0
	v_mfma_f32_16x16x32_f16 v[8:11], v[248:251], v[4:7], v[8:11]
	s_nop 2
	s_nop 4
	v_cndmask_b32_e64 v12, v8, v11, s[40:41]
	v_cndmask_b32_e64 v13, v9, v10, s[40:41]
	v_cndmask_b32_e64 v14, v10, v9, s[40:41]
	v_cndmask_b32_e64 v15, v11, v8, s[40:41]
	v_mul_f32_e32 v12, v12, v16
	v_mul_f32_e32 v13, v13, v16
	v_mul_f32_e32 v14, v14, v16
	v_mul_f32_e32 v15, v15, v16
	v_mul_f32_e32 v12, v20, v12
	v_mul_f32_e32 v13, v21, v13
	v_mul_f32_e32 v14, v22, v14
	v_mul_f32_e32 v15, v23, v15
	v_mul_f32_e32 v27, v12, v12
	v_fmac_f32_e32 v27, v13, v13
	v_fmac_f32_e32 v27, v14, v14
	v_fmac_f32_e32 v27, v15, v15
	v_add_f32_e32 v28, v28, v27
	s_mov_b64 exec, s[38:39]
	ds_write_b32 v18, v12
	ds_write_b32 v18, v13 offset:8
	ds_write_b32 v18, v14 offset:16
	ds_write_b32 v18, v15 offset:24
	s_mov_b64 exec, -1
	v_add_u32_e32 v18, v18, v19
	v_add_u32_e32 v17, 0x1f80, v25
	v_cvt_f32_i32_e32 v17, v17
	v_mul_f32_e32 v17, v93, v17
	v_mul_f32_e32 v17, 0x3fb8aa3b, v17
	v_exp_f32_e32 v16, v17
	s_waitcnt vmcnt(0)
	v_mfma_f32_16x16x32_f16 v[8:11], v[228:231], v[0:3], 0
	v_mfma_f32_16x16x32_f16 v[8:11], v[232:235], v[4:7], v[8:11]
	s_nop 2
	s_nop 4
	v_cndmask_b32_e64 v12, v8, v11, s[40:41]
	v_cndmask_b32_e64 v13, v9, v10, s[40:41]
	v_cndmask_b32_e64 v14, v10, v9, s[40:41]
	v_cndmask_b32_e64 v15, v11, v8, s[40:41]
	v_mul_f32_e32 v12, v12, v16
	v_mul_f32_e32 v13, v13, v16
	v_mul_f32_e32 v14, v14, v16
	v_mul_f32_e32 v15, v15, v16
	v_mul_f32_e32 v12, v20, v12
	v_mul_f32_e32 v13, v21, v13
	v_mul_f32_e32 v14, v22, v14
	v_mul_f32_e32 v15, v23, v15
	v_mul_f32_e32 v27, v12, v12
	v_fmac_f32_e32 v27, v13, v13
	v_fmac_f32_e32 v27, v14, v14
	v_fmac_f32_e32 v27, v15, v15
	v_add_f32_e32 v28, v28, v27
	s_mov_b64 exec, s[38:39]
	ds_write_b32 v18, v12
	ds_write_b32 v18, v13 offset:8
	ds_write_b32 v18, v14 offset:16
	ds_write_b32 v18, v15 offset:24
	s_mov_b64 exec, -1
	v_add_u32_e32 v18, v18, v19
	s_waitcnt lgkmcnt(0)
	s_and_saveexec_b64 s[12:13], s[46:47]
	s_cbranch_execz .LBB0_1316
	v_readlane_b32 s18, v253, 23
	s_nop 1
	v_mov_b32_e32 v0, s18
	ds_write_b64 v0, v[220:221]
